# adds: P7 epilogue one unconditional vmcnt(0) per conv pass instead of a wait ladder in every row-group block
# speedup vs baseline: 1.0028x; 1.0028x over previous
.LBB0_692:
	v_fmamk_f32 v198, v198, 0x3a800000, v215
	v_rsq_f32_e32 v198, v198
	s_cmp_lt_i32 s16, 32
	s_cselect_b32 s0, 2, 0xc2
	s_cmp_lg_u32 s16, 0
	v_pk_fma_f32 v[158:159], v[158:159], v[198:199], v[142:143] op_sel_hi:[1,0,1]
	v_pk_fma_f32 v[156:157], v[156:157], v[198:199], v[140:141] op_sel_hi:[1,0,1]
	v_pk_fma_f32 v[154:155], v[154:155], v[198:199], v[138:139] op_sel_hi:[1,0,1]
	v_pk_fma_f32 v[152:153], v[152:153], v[198:199], v[136:137] op_sel_hi:[1,0,1]
	s_cselect_b32 s46, s0, 0
	v_mov_b32_e32 v222, 0
	v_mov_b32_e32 v226, 0
	v_mov_b32_e32 v223, 0
	v_mov_b32_e32 v227, 0
	v_mov_b32_e32 v224, 0
	v_mov_b32_e32 v228, 0
	v_mov_b32_e32 v225, 0
	v_mov_b32_e32 v229, 0
	v_mov_b32_e32 v230, 0
	v_mov_b32_e32 v233, 0
	v_mov_b32_e32 v231, 0
	v_mov_b32_e32 v236, 0
	v_mov_b32_e32 v234, 0
	v_mov_b32_e32 v239, 0
	v_mov_b32_e32 v237, 0
	v_mov_b32_e32 v240, 0
	v_mov_b32_dpp v222, v156 row_ror:1 row_mask:0xf bank_mask:0xf
	v_mov_b32_dpp v226, v156 row_ror:2 row_mask:0xf bank_mask:0xf
	v_mov_b32_dpp v223, v157 row_ror:1 row_mask:0xf bank_mask:0xf
	v_mov_b32_dpp v227, v157 row_ror:2 row_mask:0xf bank_mask:0xf
	v_mov_b32_dpp v224, v158 row_ror:1 row_mask:0xf bank_mask:0xf
	v_mov_b32_dpp v228, v158 row_ror:2 row_mask:0xf bank_mask:0xf
	v_mov_b32_dpp v225, v159 row_ror:1 row_mask:0xf bank_mask:0xf
	v_mov_b32_dpp v229, v159 row_ror:2 row_mask:0xf bank_mask:0xf
	v_mov_b32_dpp v230, v152 row_ror:1 row_mask:0xf bank_mask:0xf
	v_mov_b32_dpp v233, v152 row_ror:2 row_mask:0xf bank_mask:0xf
	v_mov_b32_dpp v231, v153 row_ror:1 row_mask:0xf bank_mask:0xf
	v_mov_b32_dpp v236, v153 row_ror:2 row_mask:0xf bank_mask:0xf
	v_mov_b32_dpp v234, v154 row_ror:1 row_mask:0xf bank_mask:0xf
	v_mov_b32_dpp v239, v154 row_ror:2 row_mask:0xf bank_mask:0xf
	v_mov_b32_dpp v237, v155 row_ror:1 row_mask:0xf bank_mask:0xf
	v_mov_b32_dpp v240, v155 row_ror:2 row_mask:0xf bank_mask:0xf
	v_cmp_le_u32_e64 s[0:1], s46, v200
	s_waitcnt vmcnt(0)
	s_and_saveexec_b64 s[16:17], s[0:1]
	s_cbranch_execz .LBB0_694
	v_cndmask_b32_e64 v244, v244, v239, s[8:9]
	v_cndmask_b32_e64 v245, v245, v240, s[8:9]
	v_cndmask_b32_e64 v174, v234, v174, s[6:7]
	v_cndmask_b32_e64 v175, v237, v175, s[6:7]
	v_pk_mul_f32 v[244:245], v[126:127], v[244:245]
	v_cndmask_b32_e64 v170, v224, v170, s[6:7]
	v_pk_fma_f32 v[174:175], v[130:131], v[174:175], v[244:245]
	v_cndmask_b32_e64 v171, v225, v171, s[6:7]
	v_pk_fma_f32 v[154:155], v[154:155], v[134:135], v[174:175]
	v_cndmask_b32_e64 v174, v238, v228, s[8:9]
	v_cndmask_b32_e64 v175, v241, v229, s[8:9]
	v_pk_mul_f32 v[174:175], v[122:123], v[174:175]
	v_cndmask_b32_e64 v242, v242, v233, s[8:9]
	v_pk_fma_f32 v[170:171], v[114:115], v[170:171], v[174:175]
	v_cndmask_b32_e64 v243, v243, v236, s[8:9]
	v_pk_fma_f32 v[158:159], v[158:159], v[118:119], v[170:171]
	v_cndmask_b32_e64 v172, v230, v172, s[6:7]
	v_mul_f32_e32 v170, 0xbfb8aa3b, v159
	v_exp_f32_e32 v170, v170
	v_cndmask_b32_e64 v173, v231, v173, s[6:7]
	v_pk_mul_f32 v[242:243], v[124:125], v[242:243]
	v_mul_f32_e32 v171, 0xbfb8aa3b, v158
	v_add_f32_e32 v170, 1.0, v170
	v_pk_fma_f32 v[172:173], v[128:129], v[172:173], v[242:243]
	v_rcp_f32_e32 v170, v170
	v_pk_fma_f32 v[152:153], v[152:153], v[132:133], v[172:173]
	v_cndmask_b32_e64 v172, v232, v226, s[8:9]
	v_cndmask_b32_e64 v173, v235, v227, s[8:9]
	v_exp_f32_e32 v171, v171
	v_pk_mul_f32 v[172:173], v[120:121], v[172:173]
	v_cndmask_b32_e64 v168, v222, v168, s[6:7]
	v_cndmask_b32_e64 v169, v223, v169, s[6:7]
	v_pk_fma_f32 v[168:169], v[112:113], v[168:169], v[172:173]
	v_mul_f32_e32 v159, v159, v170
	v_pk_fma_f32 v[156:157], v[156:157], v[116:117], v[168:169]
	v_mul_f32_e32 v155, v159, v155
	v_add_f32_e32 v159, 1.0, v171
	v_mul_f32_e32 v168, 0xbfb8aa3b, v157
	v_mul_f32_e32 v169, 0xbfb8aa3b, v156
	v_rcp_f32_e32 v159, v159
	v_exp_f32_e32 v168, v168
	v_exp_f32_e32 v169, v169
	v_mul_f32_e32 v158, v158, v159
	v_add_f32_e32 v159, 1.0, v168
	v_add_f32_e32 v168, 1.0, v169
	v_rcp_f32_e32 v159, v159
	v_rcp_f32_e32 v168, v168
	v_mul_f32_e32 v154, v158, v154
	v_mul_f32_e32 v157, v157, v159
	v_mul_f32_e32 v156, v156, v168
	v_mul_f32_e32 v153, v157, v153
	v_mul_f32_e32 v152, v156, v152
	v_cvt_pk_bf16_f32 v152, v152, v153
	v_cvt_pk_bf16_f32 v153, v154, v155
	v_mov_b64_e32 v[154:155], s[30:31]
	v_mad_i64_i32 v[154:155], s[18:19], v194, s67, v[154:155]
	v_lshl_add_u64 v[154:155], v[192:193], 1, v[154:155]
	global_store_dwordx2 v[154:155], v[152:153], off
.LBB0_694:
	s_or_b64 exec, exec, s[16:17]
	v_fmamk_f32 v152, v221, 0x3a800000, v215
	v_rsq_f32_e32 v152, v152
	v_mov_b32_e32 v158, 0
	v_mov_b32_e32 v155, 0
	v_mov_b32_e32 v159, 0
	v_pk_fma_f32 v[150:151], v[150:151], v[152:153], v[142:143] op_sel_hi:[1,0,1]
	v_pk_fma_f32 v[148:149], v[148:149], v[152:153], v[140:141] op_sel_hi:[1,0,1]
	v_pk_fma_f32 v[146:147], v[146:147], v[152:153], v[138:139] op_sel_hi:[1,0,1]
	v_pk_fma_f32 v[144:145], v[144:145], v[152:153], v[136:137] op_sel_hi:[1,0,1]
	v_mov_b32_e32 v153, 0
	v_mov_b32_e32 v156, 0
	v_mov_b32_e32 v168, 0
	v_mov_b32_e32 v157, 0
	v_mov_b32_e32 v169, 0
	v_mov_b32_e32 v172, 0
	v_mov_b32_e32 v174, 0
	v_mov_b32_e32 v173, 0
	v_mov_b32_e32 v221, 0
	v_mov_b32_e32 v175, 0
	v_mov_b32_e32 v235, 0
	v_mov_b32_e32 v232, 0
	v_mov_b32_e32 v238, 0
	v_mov_b32_dpp v153, v148 row_ror:1 row_mask:0xf bank_mask:0xf
	v_mov_b32_dpp v158, v148 row_ror:2 row_mask:0xf bank_mask:0xf
	v_mov_b32_dpp v155, v149 row_ror:1 row_mask:0xf bank_mask:0xf
	v_mov_b32_dpp v159, v149 row_ror:2 row_mask:0xf bank_mask:0xf
	v_mov_b32_dpp v156, v150 row_ror:1 row_mask:0xf bank_mask:0xf
	v_mov_b32_dpp v168, v150 row_ror:2 row_mask:0xf bank_mask:0xf
	v_mov_b32_dpp v157, v151 row_ror:1 row_mask:0xf bank_mask:0xf
	v_mov_b32_dpp v169, v151 row_ror:2 row_mask:0xf bank_mask:0xf
	v_mov_b32_dpp v172, v144 row_ror:1 row_mask:0xf bank_mask:0xf
	v_mov_b32_dpp v174, v144 row_ror:2 row_mask:0xf bank_mask:0xf
	v_mov_b32_dpp v173, v145 row_ror:1 row_mask:0xf bank_mask:0xf
	v_mov_b32_dpp v221, v145 row_ror:2 row_mask:0xf bank_mask:0xf
	v_mov_b32_dpp v175, v146 row_ror:1 row_mask:0xf bank_mask:0xf
	v_mov_b32_dpp v235, v146 row_ror:2 row_mask:0xf bank_mask:0xf
	v_mov_b32_dpp v232, v147 row_ror:1 row_mask:0xf bank_mask:0xf
	v_mov_b32_dpp v238, v147 row_ror:2 row_mask:0xf bank_mask:0xf
	v_cmp_le_u32_e64 s[16:17], s46, v203
	v_add_u32_e32 v154, s41, v203
	s_and_saveexec_b64 s[18:19], s[16:17]
	s_cbranch_execz .LBB0_696
	v_cndmask_b32_e64 v170, v233, v174, s[8:9]
	v_cndmask_b32_e64 v171, v236, v221, s[8:9]
	v_cndmask_b32_e64 v230, v172, v230, s[6:7]
	v_cndmask_b32_e64 v231, v173, v231, s[6:7]
	v_pk_mul_f32 v[170:171], v[124:125], v[170:171]
	v_cndmask_b32_e64 v224, v156, v224, s[6:7]
	v_pk_fma_f32 v[170:171], v[128:129], v[230:231], v[170:171]
	v_cndmask_b32_e64 v225, v157, v225, s[6:7]
	v_pk_fma_f32 v[144:145], v[144:145], v[132:133], v[170:171]
	v_cndmask_b32_e64 v170, v226, v158, s[8:9]
	v_cndmask_b32_e64 v171, v227, v159, s[8:9]
	v_cndmask_b32_e64 v226, v228, v168, s[8:9]
	v_cndmask_b32_e64 v227, v229, v169, s[8:9]
	v_pk_mul_f32 v[226:227], v[122:123], v[226:227]
	v_pk_mul_f32 v[170:171], v[120:121], v[170:171]
	v_pk_fma_f32 v[224:225], v[114:115], v[224:225], v[226:227]
	v_cndmask_b32_e64 v222, v153, v222, s[6:7]
	v_pk_fma_f32 v[150:151], v[150:151], v[118:119], v[224:225]
	v_cndmask_b32_e64 v223, v155, v223, s[6:7]
	v_mul_f32_e32 v208, 0xbfb8aa3b, v151
	v_exp_f32_e32 v208, v208
	v_pk_fma_f32 v[170:171], v[112:113], v[222:223], v[170:171]
	v_mul_f32_e32 v222, 0xbfb8aa3b, v150
	v_cndmask_b32_e64 v242, v239, v235, s[8:9]
	v_add_f32_e32 v208, 1.0, v208
	v_rcp_f32_e32 v208, v208
	v_cndmask_b32_e64 v243, v240, v238, s[8:9]
	v_exp_f32_e32 v222, v222
	v_cndmask_b32_e64 v236, v175, v234, s[6:7]
	v_cndmask_b32_e64 v237, v232, v237, s[6:7]
	v_pk_mul_f32 v[240:241], v[126:127], v[242:243]
	v_pk_fma_f32 v[148:149], v[148:149], v[116:117], v[170:171]
	v_pk_fma_f32 v[236:237], v[130:131], v[236:237], v[240:241]
	v_mul_f32_e32 v151, v151, v208
	v_pk_fma_f32 v[146:147], v[146:147], v[134:135], v[236:237]
	v_mul_f32_e32 v170, 0xbfb8aa3b, v149
	v_mul_f32_e32 v147, v151, v147
	v_add_f32_e32 v151, 1.0, v222
	v_mul_f32_e32 v171, 0xbfb8aa3b, v148
	v_rcp_f32_e32 v151, v151
	v_exp_f32_e32 v170, v170
	v_exp_f32_e32 v171, v171
	v_mul_f32_e32 v150, v150, v151
	v_add_f32_e32 v151, 1.0, v170
	v_add_f32_e32 v170, 1.0, v171
	v_rcp_f32_e32 v151, v151
	v_rcp_f32_e32 v170, v170
	v_mul_f32_e32 v146, v150, v146
	v_mul_f32_e32 v149, v149, v151
	v_mul_f32_e32 v148, v148, v170
	v_mul_f32_e32 v145, v149, v145
	v_mul_f32_e32 v144, v148, v144
	v_cvt_pk_bf16_f32 v144, v144, v145
	v_cvt_pk_bf16_f32 v145, v146, v147
	v_mov_b64_e32 v[146:147], s[30:31]
	v_mad_i64_i32 v[146:147], s[20:21], v154, s67, v[146:147]
	v_lshl_add_u64 v[146:147], v[192:193], 1, v[146:147]
	global_store_dwordx2 v[146:147], v[144:145], off
.LBB0_696:
	s_or_b64 exec, exec, s[18:19]
	v_fmamk_f32 v144, v220, 0x3a800000, v215
	v_rsq_f32_e32 v144, v144
	v_mov_b32_e32 v150, 0
	v_mov_b32_e32 v146, 0
	v_mov_b32_e32 v151, 0
	v_pk_fma_f32 v[110:111], v[110:111], v[144:145], v[142:143] op_sel_hi:[1,0,1]
	v_pk_fma_f32 v[108:109], v[108:109], v[144:145], v[140:141] op_sel_hi:[1,0,1]
	v_pk_fma_f32 v[102:103], v[102:103], v[144:145], v[138:139] op_sel_hi:[1,0,1]
	v_pk_fma_f32 v[100:101], v[100:101], v[144:145], v[136:137] op_sel_hi:[1,0,1]
	v_mov_b32_e32 v145, 0
	v_mov_b32_e32 v148, 0
	v_mov_b32_e32 v170, 0
	v_mov_b32_e32 v149, 0
	v_mov_b32_e32 v171, 0
	v_mov_b32_e32 v220, 0
	v_mov_b32_e32 v223, 0
	v_mov_b32_e32 v222, 0
	v_mov_b32_e32 v225, 0
	v_mov_b32_e32 v224, 0
	v_mov_b32_e32 v227, 0
	v_mov_b32_e32 v226, 0
	v_mov_b32_e32 v228, 0
	v_mov_b32_dpp v145, v108 row_ror:1 row_mask:0xf bank_mask:0xf
	v_mov_b32_dpp v150, v108 row_ror:2 row_mask:0xf bank_mask:0xf
	v_mov_b32_dpp v146, v109 row_ror:1 row_mask:0xf bank_mask:0xf
	v_mov_b32_dpp v151, v109 row_ror:2 row_mask:0xf bank_mask:0xf
	v_mov_b32_dpp v148, v110 row_ror:1 row_mask:0xf bank_mask:0xf
	v_mov_b32_dpp v170, v110 row_ror:2 row_mask:0xf bank_mask:0xf
	v_mov_b32_dpp v149, v111 row_ror:1 row_mask:0xf bank_mask:0xf
	v_mov_b32_dpp v171, v111 row_ror:2 row_mask:0xf bank_mask:0xf
	v_mov_b32_dpp v220, v100 row_ror:1 row_mask:0xf bank_mask:0xf
	v_mov_b32_dpp v223, v100 row_ror:2 row_mask:0xf bank_mask:0xf
	v_mov_b32_dpp v222, v101 row_ror:1 row_mask:0xf bank_mask:0xf
	v_mov_b32_dpp v225, v101 row_ror:2 row_mask:0xf bank_mask:0xf
	v_mov_b32_dpp v224, v102 row_ror:1 row_mask:0xf bank_mask:0xf
	v_mov_b32_dpp v227, v102 row_ror:2 row_mask:0xf bank_mask:0xf
	v_mov_b32_dpp v226, v103 row_ror:1 row_mask:0xf bank_mask:0xf
	v_mov_b32_dpp v228, v103 row_ror:2 row_mask:0xf bank_mask:0xf
	v_cmp_le_u32_e64 s[18:19], s46, v204
	v_add_u32_e32 v147, s41, v204
	s_and_saveexec_b64 s[20:21], s[18:19]
	s_cbranch_execz .LBB0_698
	v_cndmask_b32_e64 v168, v168, v170, s[8:9]
	v_cndmask_b32_e64 v169, v169, v171, s[8:9]
	v_pk_mul_f32 v[168:169], v[122:123], v[168:169]
	v_cndmask_b32_e64 v156, v148, v156, s[6:7]
	v_cndmask_b32_e64 v157, v149, v157, s[6:7]
	v_pk_fma_f32 v[156:157], v[114:115], v[156:157], v[168:169]
	v_cndmask_b32_e64 v234, v235, v227, s[8:9]
	v_pk_fma_f32 v[110:111], v[110:111], v[118:119], v[156:157]
	v_cndmask_b32_e64 v157, v146, v155, s[6:7]
	v_mul_f32_e32 v156, 0xbfb8aa3b, v111
	v_exp_f32_e32 v168, v156
	v_cndmask_b32_e64 v156, v145, v153, s[6:7]
	v_mul_f32_e32 v155, 0xbfb8aa3b, v110
	v_cndmask_b32_e64 v235, v238, v228, s[8:9]
	v_add_f32_e32 v153, 1.0, v168
	v_rcp_f32_e32 v153, v153
	v_cndmask_b32_e64 v158, v158, v150, s[8:9]
	v_cndmask_b32_e64 v159, v159, v151, s[8:9]
	v_exp_f32_e32 v155, v155
	v_cndmask_b32_e64 v230, v174, v223, s[8:9]
	v_cndmask_b32_e64 v174, v224, v175, s[6:7]
	v_cndmask_b32_e64 v175, v226, v232, s[6:7]
	v_pk_mul_f32 v[232:233], v[126:127], v[234:235]
	v_pk_mul_f32 v[158:159], v[120:121], v[158:159]
	v_pk_fma_f32 v[174:175], v[130:131], v[174:175], v[232:233]
	v_pk_fma_f32 v[156:157], v[112:113], v[156:157], v[158:159]
	v_pk_fma_f32 v[102:103], v[102:103], v[134:135], v[174:175]
	v_pk_fma_f32 v[108:109], v[108:109], v[116:117], v[156:157]
	v_mul_f32_e32 v111, v111, v153
	v_mul_f32_e32 v103, v111, v103
	v_add_f32_e32 v111, 1.0, v155
	v_mul_f32_e32 v153, 0xbfb8aa3b, v109
	v_mul_f32_e32 v155, 0xbfb8aa3b, v108
	v_rcp_f32_e32 v111, v111
	v_exp_f32_e32 v153, v153
	v_exp_f32_e32 v155, v155
	v_cndmask_b32_e64 v231, v221, v225, s[8:9]
	v_mul_f32_e32 v110, v110, v111
	v_add_f32_e32 v111, 1.0, v153
	v_add_f32_e32 v153, 1.0, v155
	v_rcp_f32_e32 v111, v111
	v_rcp_f32_e32 v153, v153
	v_cndmask_b32_e64 v172, v220, v172, s[6:7]
	v_cndmask_b32_e64 v173, v222, v173, s[6:7]
	v_pk_mul_f32 v[230:231], v[124:125], v[230:231]
	v_mul_f32_e32 v109, v109, v111
	v_pk_fma_f32 v[172:173], v[128:129], v[172:173], v[230:231]
	v_mul_f32_e32 v108, v108, v153
	v_pk_fma_f32 v[100:101], v[100:101], v[132:133], v[172:173]
	v_mul_f32_e32 v102, v110, v102
	v_mul_f32_e32 v101, v109, v101
	v_mul_f32_e32 v100, v108, v100
	v_cvt_pk_bf16_f32 v100, v100, v101
	v_cvt_pk_bf16_f32 v101, v102, v103
	v_mov_b64_e32 v[102:103], s[30:31]
	v_mad_i64_i32 v[102:103], s[22:23], v147, s67, v[102:103]
	v_lshl_add_u64 v[102:103], v[192:193], 1, v[102:103]
	global_store_dwordx2 v[102:103], v[100:101], off
.LBB0_698:
	s_or_b64 exec, exec, s[20:21]
	v_mov_b32_e32 v100, 0
	v_mov_b32_e32 v108, 0
	v_mov_b32_e32 v101, 0
	v_mov_b32_e32 v110, 0
	v_mov_b32_e32 v102, 0
	v_mov_b32_e32 v111, 0
	v_mov_b32_e32 v103, 0
	v_mov_b32_e32 v153, 0
	v_mov_b32_e32 v155, 0
	v_mov_b32_e32 v157, 0
	v_mov_b32_e32 v156, 0
	v_mov_b32_e32 v159, 0
	v_mov_b32_e32 v158, 0
	v_mov_b32_e32 v169, 0
	v_mov_b32_e32 v168, 0
	v_mov_b32_e32 v172, 0
	v_mov_b32_dpp v100, v160 row_ror:1 row_mask:0xf bank_mask:0xf
	v_mov_b32_dpp v108, v160 row_ror:2 row_mask:0xf bank_mask:0xf
	v_mov_b32_dpp v101, v161 row_ror:1 row_mask:0xf bank_mask:0xf
	v_mov_b32_dpp v110, v161 row_ror:2 row_mask:0xf bank_mask:0xf
	v_mov_b32_dpp v102, v162 row_ror:1 row_mask:0xf bank_mask:0xf
	v_mov_b32_dpp v111, v162 row_ror:2 row_mask:0xf bank_mask:0xf
	v_mov_b32_dpp v103, v163 row_ror:1 row_mask:0xf bank_mask:0xf
	v_mov_b32_dpp v153, v163 row_ror:2 row_mask:0xf bank_mask:0xf
	v_mov_b32_dpp v155, v164 row_ror:1 row_mask:0xf bank_mask:0xf
	v_mov_b32_dpp v157, v164 row_ror:2 row_mask:0xf bank_mask:0xf
	v_mov_b32_dpp v156, v165 row_ror:1 row_mask:0xf bank_mask:0xf
	v_mov_b32_dpp v159, v165 row_ror:2 row_mask:0xf bank_mask:0xf
	v_mov_b32_dpp v158, v166 row_ror:1 row_mask:0xf bank_mask:0xf
	v_mov_b32_dpp v169, v166 row_ror:2 row_mask:0xf bank_mask:0xf
	v_mov_b32_dpp v168, v167 row_ror:1 row_mask:0xf bank_mask:0xf
	v_mov_b32_dpp v172, v167 row_ror:2 row_mask:0xf bank_mask:0xf
	v_cmp_le_u32_e64 s[20:21], s46, v205
	v_add_u32_e32 v109, s41, v205
	s_and_saveexec_b64 s[22:23], s[20:21]
	s_cbranch_execz .LBB0_700
	v_cndmask_b32_e64 v151, v151, v110, s[8:9]
	v_cndmask_b32_e64 v110, v170, v111, s[8:9]
	v_cndmask_b32_e64 v111, v171, v153, s[8:9]
	v_pk_mul_f32 v[110:111], v[122:123], v[110:111]
	v_cndmask_b32_e64 v102, v102, v148, s[6:7]
	v_cndmask_b32_e64 v103, v103, v149, s[6:7]
	v_pk_fma_f32 v[102:103], v[114:115], v[102:103], v[110:111]
	v_cndmask_b32_e64 v150, v150, v108, s[8:9]
	v_pk_fma_f32 v[102:103], v[162:163], v[118:119], v[102:103]
	v_pk_mul_f32 v[150:151], v[120:121], v[150:151]
	v_mul_f32_e32 v108, 0xbfb8aa3b, v103
	v_exp_f32_e32 v108, v108
	v_mul_f32_e32 v110, 0xbfb8aa3b, v102
	v_exp_f32_e32 v110, v110
	v_cndmask_b32_e64 v100, v100, v145, s[6:7]
	v_add_f32_e32 v108, 1.0, v108
	v_rcp_f32_e32 v108, v108
	v_cndmask_b32_e64 v101, v101, v146, s[6:7]
	v_pk_fma_f32 v[100:101], v[112:113], v[100:101], v[150:151]
	v_cndmask_b32_e64 v174, v223, v157, s[8:9]
	v_pk_fma_f32 v[100:101], v[160:161], v[116:117], v[100:101]
	v_mul_f32_e32 v103, v103, v108
	v_add_f32_e32 v108, 1.0, v110
	v_mul_f32_e32 v110, 0xbfb8aa3b, v101
	v_mul_f32_e32 v111, 0xbfb8aa3b, v100
	v_rcp_f32_e32 v108, v108
	v_exp_f32_e32 v110, v110
	v_exp_f32_e32 v111, v111
	v_cndmask_b32_e64 v175, v225, v159, s[8:9]
	v_mul_f32_e32 v102, v102, v108
	v_add_f32_e32 v108, 1.0, v110
	v_add_f32_e32 v110, 1.0, v111
	v_rcp_f32_e32 v108, v108
	v_rcp_f32_e32 v110, v110
	v_cndmask_b32_e64 v230, v227, v169, s[8:9]
	v_cndmask_b32_e64 v231, v228, v172, s[8:9]
	v_cndmask_b32_e64 v172, v155, v220, s[6:7]
	v_cndmask_b32_e64 v173, v156, v222, s[6:7]
	v_cndmask_b32_e64 v156, v158, v224, s[6:7]
	v_cndmask_b32_e64 v157, v168, v226, s[6:7]
	v_pk_mul_f32 v[158:159], v[124:125], v[174:175]
	v_pk_mul_f32 v[168:169], v[126:127], v[230:231]
	v_pk_fma_f32 v[158:159], v[128:129], v[172:173], v[158:159]
	v_pk_fma_f32 v[156:157], v[130:131], v[156:157], v[168:169]
	v_pk_fma_f32 v[158:159], v[164:165], v[132:133], v[158:159]
	v_pk_fma_f32 v[156:157], v[166:167], v[134:135], v[156:157]
	v_mul_f32_e32 v101, v101, v108
	v_mul_f32_e32 v100, v100, v110
	v_mul_f32_e32 v103, v103, v157
	v_mul_f32_e32 v102, v102, v156
	v_mul_f32_e32 v101, v101, v159
	v_mul_f32_e32 v100, v100, v158
	v_cvt_pk_bf16_f32 v100, v100, v101
	v_cvt_pk_bf16_f32 v101, v102, v103
	v_mov_b64_e32 v[102:103], s[30:31]
	v_mad_i64_i32 v[102:103], s[24:25], v109, s67, v[102:103]
	v_lshl_add_u64 v[102:103], v[192:193], 1, v[102:103]
	global_store_dwordx2 v[102:103], v[100:101], off
.LBB0_700:
	s_or_b64 exec, exec, s[22:23]
	v_fmamk_f32 v100, v219, 0x3a800000, v215
	v_rsq_f32_e32 v108, v100
	v_mov_b32_e32 v100, 0
	v_mov_b32_e32 v110, 0
	v_mov_b32_e32 v101, 0
	v_pk_fma_f32 v[94:95], v[94:95], v[108:109], v[142:143] op_sel_hi:[1,0,1]
	v_pk_fma_f32 v[92:93], v[92:93], v[108:109], v[140:141] op_sel_hi:[1,0,1]
	v_pk_fma_f32 v[90:91], v[90:91], v[108:109], v[138:139] op_sel_hi:[1,0,1]
	v_pk_fma_f32 v[88:89], v[88:89], v[108:109], v[136:137] op_sel_hi:[1,0,1]
	v_mov_b32_e32 v145, 0
	v_mov_b32_e32 v102, 0
	v_mov_b32_e32 v150, 0
	v_mov_b32_e32 v103, 0
	v_mov_b32_e32 v151, 0
	v_mov_b32_e32 v153, 0
	v_mov_b32_e32 v156, 0
	v_mov_b32_e32 v155, 0
	v_mov_b32_e32 v158, 0
	v_mov_b32_e32 v157, 0
	v_mov_b32_e32 v160, 0
	v_mov_b32_e32 v159, 0
	v_mov_b32_e32 v161, 0
	v_mov_b32_dpp v100, v92 row_ror:1 row_mask:0xf bank_mask:0xf
	v_mov_b32_dpp v110, v92 row_ror:2 row_mask:0xf bank_mask:0xf
	v_mov_b32_dpp v101, v93 row_ror:1 row_mask:0xf bank_mask:0xf
	v_mov_b32_dpp v145, v93 row_ror:2 row_mask:0xf bank_mask:0xf
	v_mov_b32_dpp v102, v94 row_ror:1 row_mask:0xf bank_mask:0xf
	v_mov_b32_dpp v150, v94 row_ror:2 row_mask:0xf bank_mask:0xf
	v_mov_b32_dpp v103, v95 row_ror:1 row_mask:0xf bank_mask:0xf
	v_mov_b32_dpp v151, v95 row_ror:2 row_mask:0xf bank_mask:0xf
	v_mov_b32_dpp v153, v88 row_ror:1 row_mask:0xf bank_mask:0xf
	v_mov_b32_dpp v156, v88 row_ror:2 row_mask:0xf bank_mask:0xf
	v_mov_b32_dpp v155, v89 row_ror:1 row_mask:0xf bank_mask:0xf
	v_mov_b32_dpp v158, v89 row_ror:2 row_mask:0xf bank_mask:0xf
	v_mov_b32_dpp v157, v90 row_ror:1 row_mask:0xf bank_mask:0xf
	v_mov_b32_dpp v160, v90 row_ror:2 row_mask:0xf bank_mask:0xf
	v_mov_b32_dpp v159, v91 row_ror:1 row_mask:0xf bank_mask:0xf
	v_mov_b32_dpp v161, v91 row_ror:2 row_mask:0xf bank_mask:0xf
	v_cmp_le_u32_e64 s[22:23], s46, v206
	v_add_u32_e32 v149, s64, v202
	v_add_u32_e32 v111, s41, v206
	s_and_saveexec_b64 s[24:25], s[22:23]
	s_cbranch_execz .LBB0_702
	ds_read_b128 v[162:165], v149 offset:288
	ds_read_b128 v[166:169], v149 offset:32
	ds_read_b128 v[170:173], v149
	ds_read_b128 v[220:223], v149 offset:256
	s_waitcnt lgkmcnt(2)
	v_cndmask_b32_e64 v146, v165, v169, s[6:7]
	v_cndmask_b32_e64 v148, v164, v168, s[6:7]
	v_cndmask_b32_e64 v168, v148, v160, s[8:9]
	v_cndmask_b32_e64 v169, v146, v161, s[8:9]
	v_cndmask_b32_e64 v167, v163, v167, s[6:7]
	v_cndmask_b32_e64 v166, v162, v166, s[6:7]
	v_cndmask_b32_e64 v164, v157, v164, s[6:7]
	v_cndmask_b32_e64 v165, v159, v165, s[6:7]
	v_pk_mul_f32 v[168:169], v[126:127], v[168:169]
	v_cndmask_b32_e64 v166, v166, v156, s[8:9]
	v_cndmask_b32_e64 v167, v167, v158, s[8:9]
	v_pk_fma_f32 v[164:165], v[130:131], v[164:165], v[168:169]
	s_waitcnt lgkmcnt(0)
	v_cndmask_b32_e64 v146, v223, v173, s[6:7]
	v_cndmask_b32_e64 v148, v222, v172, s[6:7]
	v_cndmask_b32_e64 v162, v153, v162, s[6:7]
	v_cndmask_b32_e64 v163, v155, v163, s[6:7]
	v_pk_mul_f32 v[166:167], v[124:125], v[166:167]
	v_pk_fma_f32 v[90:91], v[90:91], v[134:135], v[164:165]
	v_cndmask_b32_e64 v164, v148, v150, s[8:9]
	v_cndmask_b32_e64 v165, v146, v151, s[8:9]
	v_pk_fma_f32 v[162:163], v[128:129], v[162:163], v[166:167]
	v_pk_mul_f32 v[164:165], v[122:123], v[164:165]
	v_cndmask_b32_e64 v166, v102, v222, s[6:7]
	v_cndmask_b32_e64 v167, v103, v223, s[6:7]
	v_pk_fma_f32 v[164:165], v[114:115], v[166:167], v[164:165]
	v_pk_fma_f32 v[88:89], v[88:89], v[132:133], v[162:163]
	v_pk_fma_f32 v[94:95], v[94:95], v[118:119], v[164:165]
	v_cndmask_b32_e64 v163, v221, v171, s[6:7]
	v_mul_f32_e32 v146, 0xbfb8aa3b, v95
	v_exp_f32_e32 v146, v146
	v_cndmask_b32_e64 v162, v220, v170, s[6:7]
	v_mul_f32_e32 v148, 0xbfb8aa3b, v94
	v_cndmask_b32_e64 v162, v162, v110, s[8:9]
	v_add_f32_e32 v146, 1.0, v146
	v_rcp_f32_e32 v146, v146
	v_cndmask_b32_e64 v163, v163, v145, s[8:9]
	v_exp_f32_e32 v148, v148
	v_pk_mul_f32 v[162:163], v[120:121], v[162:163]
	v_cndmask_b32_e64 v164, v100, v220, s[6:7]
	v_cndmask_b32_e64 v165, v101, v221, s[6:7]
	v_pk_fma_f32 v[162:163], v[112:113], v[164:165], v[162:163]
	v_mul_f32_e32 v95, v95, v146
	v_pk_fma_f32 v[92:93], v[92:93], v[116:117], v[162:163]
	v_mul_f32_e32 v91, v91, v95
	v_add_f32_e32 v95, 1.0, v148
	v_mul_f32_e32 v146, 0xbfb8aa3b, v93
	v_mul_f32_e32 v148, 0xbfb8aa3b, v92
	v_rcp_f32_e32 v95, v95
	v_exp_f32_e32 v146, v146
	v_exp_f32_e32 v148, v148
	v_mul_f32_e32 v94, v94, v95
	v_add_f32_e32 v95, 1.0, v146
	v_add_f32_e32 v146, 1.0, v148
	v_rcp_f32_e32 v95, v95
	v_rcp_f32_e32 v146, v146
	v_mul_f32_e32 v90, v90, v94
	v_mul_f32_e32 v93, v93, v95
	v_mul_f32_e32 v92, v92, v146
	v_mul_f32_e32 v89, v89, v93
	v_mul_f32_e32 v88, v88, v92
	v_cvt_pk_bf16_f32 v88, v88, v89
	v_cvt_pk_bf16_f32 v89, v90, v91
	v_mov_b64_e32 v[90:91], s[30:31]
	v_mad_i64_i32 v[90:91], s[26:27], v111, s67, v[90:91]
	v_lshl_add_u64 v[90:91], v[192:193], 1, v[90:91]
	global_store_dwordx2 v[90:91], v[88:89], off
.LBB0_702:
	s_or_b64 exec, exec, s[24:25]
	v_fmamk_f32 v88, v218, 0x3a800000, v215
	v_rsq_f32_e32 v146, v88
	v_mov_b32_e32 v88, 0
	v_mov_b32_e32 v92, 0
	v_mov_b32_e32 v89, 0
	v_pk_fma_f32 v[86:87], v[86:87], v[146:147], v[142:143] op_sel_hi:[1,0,1]
	v_pk_fma_f32 v[84:85], v[84:85], v[146:147], v[140:141] op_sel_hi:[1,0,1]
	v_pk_fma_f32 v[82:83], v[82:83], v[146:147], v[138:139] op_sel_hi:[1,0,1]
	v_pk_fma_f32 v[80:81], v[80:81], v[146:147], v[136:137] op_sel_hi:[1,0,1]
	v_mov_b32_e32 v93, 0
	v_mov_b32_e32 v90, 0
	v_mov_b32_e32 v94, 0
	v_mov_b32_e32 v91, 0
	v_mov_b32_e32 v95, 0
	v_mov_b32_e32 v162, 0
	v_mov_b32_e32 v164, 0
	v_mov_b32_e32 v163, 0
	v_mov_b32_e32 v166, 0
	v_mov_b32_e32 v165, 0
	v_mov_b32_e32 v168, 0
	v_mov_b32_e32 v167, 0
	v_mov_b32_e32 v169, 0
	v_mov_b32_dpp v88, v84 row_ror:1 row_mask:0xf bank_mask:0xf
	v_mov_b32_dpp v92, v84 row_ror:2 row_mask:0xf bank_mask:0xf
	v_mov_b32_dpp v89, v85 row_ror:1 row_mask:0xf bank_mask:0xf
	v_mov_b32_dpp v93, v85 row_ror:2 row_mask:0xf bank_mask:0xf
	v_mov_b32_dpp v90, v86 row_ror:1 row_mask:0xf bank_mask:0xf
	v_mov_b32_dpp v94, v86 row_ror:2 row_mask:0xf bank_mask:0xf
	v_mov_b32_dpp v91, v87 row_ror:1 row_mask:0xf bank_mask:0xf
	v_mov_b32_dpp v95, v87 row_ror:2 row_mask:0xf bank_mask:0xf
	v_mov_b32_dpp v162, v80 row_ror:1 row_mask:0xf bank_mask:0xf
	v_mov_b32_dpp v164, v80 row_ror:2 row_mask:0xf bank_mask:0xf
	v_mov_b32_dpp v163, v81 row_ror:1 row_mask:0xf bank_mask:0xf
	v_mov_b32_dpp v166, v81 row_ror:2 row_mask:0xf bank_mask:0xf
	v_mov_b32_dpp v165, v82 row_ror:1 row_mask:0xf bank_mask:0xf
	v_mov_b32_dpp v168, v82 row_ror:2 row_mask:0xf bank_mask:0xf
	v_mov_b32_dpp v167, v83 row_ror:1 row_mask:0xf bank_mask:0xf
	v_mov_b32_dpp v169, v83 row_ror:2 row_mask:0xf bank_mask:0xf
	v_cmp_le_u32_e64 s[24:25], s46, v207
	v_add_u32_e32 v148, s41, v207
	s_and_saveexec_b64 s[26:27], s[24:25]
	s_cbranch_execz .LBB0_704
	v_cndmask_b32_e64 v150, v150, v94, s[8:9]
	v_cndmask_b32_e64 v151, v151, v95, s[8:9]
	v_pk_mul_f32 v[150:151], v[122:123], v[150:151]
	v_cndmask_b32_e64 v102, v90, v102, s[6:7]
	v_cndmask_b32_e64 v103, v91, v103, s[6:7]
	v_pk_fma_f32 v[102:103], v[114:115], v[102:103], v[150:151]
	v_cndmask_b32_e64 v160, v160, v168, s[8:9]
	v_pk_fma_f32 v[86:87], v[86:87], v[118:119], v[102:103]
	v_cndmask_b32_e64 v161, v161, v169, s[8:9]
	v_mul_f32_e32 v102, 0xbfb8aa3b, v87
	v_exp_f32_e32 v102, v102
	v_cndmask_b32_e64 v170, v156, v164, s[8:9]
	v_cndmask_b32_e64 v156, v165, v157, s[6:7]
	v_cndmask_b32_e64 v157, v167, v159, s[6:7]
	v_pk_mul_f32 v[160:161], v[126:127], v[160:161]
	v_add_f32_e32 v102, 1.0, v102
	v_pk_fma_f32 v[156:157], v[130:131], v[156:157], v[160:161]
	v_rcp_f32_e32 v102, v102
	v_mul_f32_e32 v103, 0xbfb8aa3b, v86
	v_pk_fma_f32 v[82:83], v[82:83], v[134:135], v[156:157]
	v_cndmask_b32_e64 v156, v110, v92, s[8:9]
	v_cndmask_b32_e64 v157, v145, v93, s[8:9]
	v_exp_f32_e32 v103, v103
	v_pk_mul_f32 v[156:157], v[120:121], v[156:157]
	v_cndmask_b32_e64 v100, v88, v100, s[6:7]
	v_cndmask_b32_e64 v101, v89, v101, s[6:7]
	v_pk_fma_f32 v[100:101], v[112:113], v[100:101], v[156:157]
	v_mul_f32_e32 v87, v87, v102
	v_pk_fma_f32 v[84:85], v[84:85], v[116:117], v[100:101]
	v_mul_f32_e32 v83, v87, v83
	v_add_f32_e32 v87, 1.0, v103
	v_mul_f32_e32 v100, 0xbfb8aa3b, v85
	v_mul_f32_e32 v101, 0xbfb8aa3b, v84
	v_rcp_f32_e32 v87, v87
	v_exp_f32_e32 v100, v100
	v_exp_f32_e32 v101, v101
	v_cndmask_b32_e64 v171, v158, v166, s[8:9]
	v_mul_f32_e32 v86, v86, v87
	v_add_f32_e32 v87, 1.0, v100
	v_add_f32_e32 v100, 1.0, v101
	v_rcp_f32_e32 v87, v87
	v_rcp_f32_e32 v100, v100
	v_cndmask_b32_e64 v172, v162, v153, s[6:7]
	v_cndmask_b32_e64 v173, v163, v155, s[6:7]
	v_pk_mul_f32 v[158:159], v[124:125], v[170:171]
	v_mul_f32_e32 v85, v85, v87
	v_pk_fma_f32 v[158:159], v[128:129], v[172:173], v[158:159]
	v_mul_f32_e32 v84, v84, v100
	v_pk_fma_f32 v[80:81], v[80:81], v[132:133], v[158:159]
	v_mul_f32_e32 v82, v86, v82
	v_mul_f32_e32 v81, v85, v81
	v_mul_f32_e32 v80, v84, v80
	v_cvt_pk_bf16_f32 v80, v80, v81
	v_cvt_pk_bf16_f32 v81, v82, v83
	v_mov_b64_e32 v[82:83], s[30:31]
	v_mad_i64_i32 v[82:83], s[28:29], v148, s67, v[82:83]
	v_lshl_add_u64 v[82:83], v[192:193], 1, v[82:83]
	global_store_dwordx2 v[82:83], v[80:81], off
.LBB0_704:
	s_or_b64 exec, exec, s[26:27]
	v_fmamk_f32 v80, v199, 0x3a800000, v215
	v_rsq_f32_e32 v110, v80
	v_mov_b32_e32 v80, 0
	v_mov_b32_e32 v84, 0
	v_mov_b32_e32 v81, 0
	v_pk_fma_f32 v[78:79], v[78:79], v[110:111], v[142:143] op_sel_hi:[1,0,1]
	v_pk_fma_f32 v[76:77], v[76:77], v[110:111], v[140:141] op_sel_hi:[1,0,1]
	v_pk_fma_f32 v[74:75], v[74:75], v[110:111], v[138:139] op_sel_hi:[1,0,1]
	v_pk_fma_f32 v[72:73], v[72:73], v[110:111], v[136:137] op_sel_hi:[1,0,1]
	v_mov_b32_e32 v85, 0
	v_mov_b32_e32 v82, 0
	v_mov_b32_e32 v86, 0
	v_mov_b32_e32 v83, 0
	v_mov_b32_e32 v87, 0
	v_mov_b32_e32 v100, 0
	v_mov_b32_e32 v102, 0
	v_mov_b32_e32 v101, 0
	v_mov_b32_e32 v138, 0
	v_mov_b32_e32 v103, 0
	v_mov_b32_e32 v140, 0
	v_mov_b32_e32 v139, 0
	v_mov_b32_e32 v141, 0
	v_mov_b32_dpp v80, v76 row_ror:1 row_mask:0xf bank_mask:0xf
	v_mov_b32_dpp v84, v76 row_ror:2 row_mask:0xf bank_mask:0xf
	v_mov_b32_dpp v81, v77 row_ror:1 row_mask:0xf bank_mask:0xf
	v_mov_b32_dpp v85, v77 row_ror:2 row_mask:0xf bank_mask:0xf
	v_mov_b32_dpp v82, v78 row_ror:1 row_mask:0xf bank_mask:0xf
	v_mov_b32_dpp v86, v78 row_ror:2 row_mask:0xf bank_mask:0xf
	v_mov_b32_dpp v83, v79 row_ror:1 row_mask:0xf bank_mask:0xf
	v_mov_b32_dpp v87, v79 row_ror:2 row_mask:0xf bank_mask:0xf
	v_mov_b32_dpp v100, v72 row_ror:1 row_mask:0xf bank_mask:0xf
	v_mov_b32_dpp v102, v72 row_ror:2 row_mask:0xf bank_mask:0xf
	v_mov_b32_dpp v101, v73 row_ror:1 row_mask:0xf bank_mask:0xf
	v_mov_b32_dpp v138, v73 row_ror:2 row_mask:0xf bank_mask:0xf
	v_mov_b32_dpp v103, v74 row_ror:1 row_mask:0xf bank_mask:0xf
	v_mov_b32_dpp v140, v74 row_ror:2 row_mask:0xf bank_mask:0xf
	v_mov_b32_dpp v139, v75 row_ror:1 row_mask:0xf bank_mask:0xf
	v_mov_b32_dpp v141, v75 row_ror:2 row_mask:0xf bank_mask:0xf
	v_cmp_le_u32_e64 s[26:27], s46, v209
	v_add_u32_e32 v136, s41, v209
	s_and_saveexec_b64 s[28:29], s[26:27]
	s_cbranch_execz .LBB0_706
	v_cndmask_b32_e64 v94, v94, v86, s[8:9]
	v_cndmask_b32_e64 v95, v95, v87, s[8:9]
	v_pk_mul_f32 v[94:95], v[122:123], v[94:95]
	v_cndmask_b32_e64 v90, v82, v90, s[6:7]
	v_cndmask_b32_e64 v91, v83, v91, s[6:7]
	v_pk_fma_f32 v[90:91], v[114:115], v[90:91], v[94:95]
	v_cndmask_b32_e64 v150, v168, v140, s[8:9]
	v_pk_fma_f32 v[78:79], v[78:79], v[118:119], v[90:91]
	v_cndmask_b32_e64 v151, v169, v141, s[8:9]
	v_mul_f32_e32 v90, 0xbfb8aa3b, v79
	v_exp_f32_e32 v90, v90
	v_mul_f32_e32 v91, 0xbfb8aa3b, v78
	v_cndmask_b32_e64 v92, v92, v84, s[8:9]
	v_cndmask_b32_e64 v93, v93, v85, s[8:9]
	v_add_f32_e32 v90, 1.0, v90
	v_rcp_f32_e32 v90, v90
	v_exp_f32_e32 v91, v91
	v_cndmask_b32_e64 v158, v103, v165, s[6:7]
	v_cndmask_b32_e64 v159, v139, v167, s[6:7]
	v_pk_mul_f32 v[150:151], v[126:127], v[150:151]
	v_pk_mul_f32 v[92:93], v[120:121], v[92:93]
	v_cndmask_b32_e64 v88, v80, v88, s[6:7]
	v_cndmask_b32_e64 v89, v81, v89, s[6:7]
	v_pk_fma_f32 v[150:151], v[130:131], v[158:159], v[150:151]
	v_pk_fma_f32 v[88:89], v[112:113], v[88:89], v[92:93]
	v_pk_fma_f32 v[74:75], v[74:75], v[134:135], v[150:151]
	v_pk_fma_f32 v[76:77], v[76:77], v[116:117], v[88:89]
	v_mul_f32_e32 v79, v79, v90
	v_mul_f32_e32 v75, v79, v75
	v_add_f32_e32 v79, 1.0, v91
	v_mul_f32_e32 v88, 0xbfb8aa3b, v77
	v_mul_f32_e32 v89, 0xbfb8aa3b, v76
	v_rcp_f32_e32 v79, v79
	v_exp_f32_e32 v88, v88
	v_exp_f32_e32 v89, v89
	v_cndmask_b32_e64 v142, v164, v102, s[8:9]
	v_mul_f32_e32 v78, v78, v79
	v_add_f32_e32 v79, 1.0, v88
	v_add_f32_e32 v88, 1.0, v89
	v_rcp_f32_e32 v79, v79
	v_rcp_f32_e32 v88, v88
	v_cndmask_b32_e64 v143, v166, v138, s[8:9]
	v_cndmask_b32_e64 v156, v100, v162, s[6:7]
	v_cndmask_b32_e64 v157, v101, v163, s[6:7]
	v_pk_mul_f32 v[142:143], v[124:125], v[142:143]
	v_mul_f32_e32 v77, v77, v79
	v_pk_fma_f32 v[142:143], v[128:129], v[156:157], v[142:143]
	v_mul_f32_e32 v76, v76, v88
	v_pk_fma_f32 v[72:73], v[72:73], v[132:133], v[142:143]
	v_mul_f32_e32 v74, v78, v74
	v_mul_f32_e32 v73, v77, v73
	v_mul_f32_e32 v72, v76, v72
	v_cvt_pk_bf16_f32 v72, v72, v73
	v_cvt_pk_bf16_f32 v73, v74, v75
	v_mov_b64_e32 v[74:75], s[30:31]
	v_mad_i64_i32 v[74:75], s[70:71], v136, s67, v[74:75]
	v_lshl_add_u64 v[74:75], v[192:193], 1, v[74:75]
	global_store_dwordx2 v[74:75], v[72:73], off
.LBB0_706:
	s_or_b64 exec, exec, s[28:29]
	v_mov_b32_e32 v72, 0
	v_mov_b32_e32 v76, 0
	v_mov_b32_e32 v73, 0
	v_mov_b32_e32 v77, 0
	v_mov_b32_e32 v74, 0
	v_mov_b32_e32 v78, 0
	v_mov_b32_e32 v75, 0
	v_mov_b32_e32 v79, 0
	v_mov_b32_e32 v88, 0
	v_mov_b32_e32 v90, 0
	v_mov_b32_e32 v89, 0
	v_mov_b32_e32 v92, 0
	v_mov_b32_e32 v91, 0
	v_mov_b32_e32 v94, 0
	v_mov_b32_e32 v93, 0
	v_mov_b32_e32 v95, 0
	v_mov_b32_dpp v72, v96 row_ror:1 row_mask:0xf bank_mask:0xf
	v_mov_b32_dpp v76, v96 row_ror:2 row_mask:0xf bank_mask:0xf
	v_mov_b32_dpp v73, v97 row_ror:1 row_mask:0xf bank_mask:0xf
	v_mov_b32_dpp v77, v97 row_ror:2 row_mask:0xf bank_mask:0xf
	v_mov_b32_dpp v74, v98 row_ror:1 row_mask:0xf bank_mask:0xf
	v_mov_b32_dpp v78, v98 row_ror:2 row_mask:0xf bank_mask:0xf
	v_mov_b32_dpp v75, v99 row_ror:1 row_mask:0xf bank_mask:0xf
	v_mov_b32_dpp v79, v99 row_ror:2 row_mask:0xf bank_mask:0xf
	v_mov_b32_dpp v88, v104 row_ror:1 row_mask:0xf bank_mask:0xf
	v_mov_b32_dpp v90, v104 row_ror:2 row_mask:0xf bank_mask:0xf
	v_mov_b32_dpp v89, v105 row_ror:1 row_mask:0xf bank_mask:0xf
	v_mov_b32_dpp v92, v105 row_ror:2 row_mask:0xf bank_mask:0xf
	v_mov_b32_dpp v91, v106 row_ror:1 row_mask:0xf bank_mask:0xf
	v_mov_b32_dpp v94, v106 row_ror:2 row_mask:0xf bank_mask:0xf
	v_mov_b32_dpp v93, v107 row_ror:1 row_mask:0xf bank_mask:0xf
	v_mov_b32_dpp v95, v107 row_ror:2 row_mask:0xf bank_mask:0xf
	v_cmp_le_u32_e64 s[28:29], s46, v210
	v_add_u32_e32 v137, s41, v210
	s_and_saveexec_b64 s[46:47], s[28:29]
	s_cbranch_execz .LBB0_708
	v_cndmask_b32_e64 v78, v86, v78, s[8:9]
	v_cndmask_b32_e64 v79, v87, v79, s[8:9]
	v_pk_mul_f32 v[78:79], v[122:123], v[78:79]
	v_cndmask_b32_e64 v74, v74, v82, s[6:7]
	v_cndmask_b32_e64 v75, v75, v83, s[6:7]
	v_pk_fma_f32 v[74:75], v[114:115], v[74:75], v[78:79]
	v_cndmask_b32_e64 v76, v84, v76, s[8:9]
	v_pk_fma_f32 v[74:75], v[98:99], v[118:119], v[74:75]
	v_cndmask_b32_e64 v77, v85, v77, s[8:9]
	v_mul_f32_e32 v78, 0xbfb8aa3b, v75
	v_exp_f32_e32 v78, v78
	v_pk_mul_f32 v[76:77], v[120:121], v[76:77]
	v_cndmask_b32_e64 v72, v72, v80, s[6:7]
	v_cndmask_b32_e64 v73, v73, v81, s[6:7]
	v_pk_fma_f32 v[72:73], v[112:113], v[72:73], v[76:77]
	v_add_f32_e32 v76, 1.0, v78
	v_mul_f32_e32 v77, 0xbfb8aa3b, v74
	v_rcp_f32_e32 v76, v76
	v_exp_f32_e32 v77, v77
	v_pk_fma_f32 v[72:73], v[96:97], v[116:117], v[72:73]
	v_cndmask_b32_e64 v142, v102, v90, s[8:9]
	v_mul_f32_e32 v75, v75, v76
	v_add_f32_e32 v76, 1.0, v77
	v_mul_f32_e32 v77, 0xbfb8aa3b, v73
	v_mul_f32_e32 v78, 0xbfb8aa3b, v72
	v_rcp_f32_e32 v76, v76
	v_exp_f32_e32 v77, v77
	v_exp_f32_e32 v78, v78
	v_cndmask_b32_e64 v143, v138, v92, s[8:9]
	v_mul_f32_e32 v74, v74, v76
	v_add_f32_e32 v76, 1.0, v77
	v_add_f32_e32 v77, 1.0, v78
	v_rcp_f32_e32 v76, v76
	v_rcp_f32_e32 v77, v77
	v_cndmask_b32_e64 v94, v140, v94, s[8:9]
	v_cndmask_b32_e64 v95, v141, v95, s[8:9]
	v_cndmask_b32_e64 v88, v88, v100, s[6:7]
	v_cndmask_b32_e64 v89, v89, v101, s[6:7]
	v_cndmask_b32_e64 v90, v91, v103, s[6:7]
	v_cndmask_b32_e64 v91, v93, v139, s[6:7]
	v_pk_mul_f32 v[92:93], v[124:125], v[142:143]
	v_pk_mul_f32 v[94:95], v[126:127], v[94:95]
	v_pk_fma_f32 v[88:89], v[128:129], v[88:89], v[92:93]
	v_pk_fma_f32 v[90:91], v[130:131], v[90:91], v[94:95]
	v_pk_fma_f32 v[88:89], v[104:105], v[132:133], v[88:89]
	v_pk_fma_f32 v[90:91], v[106:107], v[134:135], v[90:91]
	v_mul_f32_e32 v73, v73, v76
	v_mul_f32_e32 v72, v72, v77
	v_mul_f32_e32 v75, v75, v91
	v_mul_f32_e32 v74, v74, v90
	v_mul_f32_e32 v73, v73, v89
	v_mul_f32_e32 v72, v72, v88
	v_cvt_pk_bf16_f32 v72, v72, v73
	v_cvt_pk_bf16_f32 v73, v74, v75
	v_mov_b64_e32 v[74:75], s[30:31]
	v_mad_i64_i32 v[74:75], s[70:71], v137, s67, v[74:75]
	v_lshl_add_u64 v[74:75], v[192:193], 1, v[74:75]
	global_store_dwordx2 v[74:75], v[72:73], off

.LBB0_710:
	v_mov_b32_e32 v199, v198
	v_mov_b32_e32 v104, v198
	v_mov_b32_e32 v105, v198
	v_pk_fma_f32 v[62:63], v[62:63], v[104:105], v[46:47]
	v_pk_fma_f32 v[60:61], v[60:61], v[198:199], v[44:45]
	v_pk_fma_f32 v[58:59], v[58:59], v[104:105], v[42:43]
	v_pk_fma_f32 v[56:57], v[56:57], v[198:199], v[40:41]
	v_mov_b32_e32 v104, 0
	v_mov_b32_e32 v112, 0
	v_mov_b32_e32 v105, 0
	v_mov_b32_e32 v113, 0
	v_mov_b32_e32 v106, 0
	v_mov_b32_e32 v114, 0
	v_mov_b32_e32 v107, 0
	v_mov_b32_e32 v115, 0
	s_waitcnt vmcnt(7)
	v_mov_b32_e32 v116, 0
	v_mov_b32_e32 v118, 0
	v_mov_b32_e32 v117, 0
	v_mov_b32_e32 v120, 0
	v_mov_b32_e32 v119, 0
	v_mov_b32_e32 v122, 0
	v_mov_b32_e32 v121, 0
	v_mov_b32_e32 v123, 0
	v_mov_b32_dpp v104, v60 row_ror:1 row_mask:0xf bank_mask:0xf
	v_mov_b32_dpp v112, v60 row_ror:2 row_mask:0xf bank_mask:0xf
	v_mov_b32_dpp v105, v61 row_ror:1 row_mask:0xf bank_mask:0xf
	v_mov_b32_dpp v113, v61 row_ror:2 row_mask:0xf bank_mask:0xf
	v_mov_b32_dpp v106, v62 row_ror:1 row_mask:0xf bank_mask:0xf
	v_mov_b32_dpp v114, v62 row_ror:2 row_mask:0xf bank_mask:0xf
	v_mov_b32_dpp v107, v63 row_ror:1 row_mask:0xf bank_mask:0xf
	v_mov_b32_dpp v115, v63 row_ror:2 row_mask:0xf bank_mask:0xf
	v_mov_b32_dpp v116, v56 row_ror:1 row_mask:0xf bank_mask:0xf
	v_mov_b32_dpp v118, v56 row_ror:2 row_mask:0xf bank_mask:0xf
	v_mov_b32_dpp v117, v57 row_ror:1 row_mask:0xf bank_mask:0xf
	v_mov_b32_dpp v120, v57 row_ror:2 row_mask:0xf bank_mask:0xf
	v_mov_b32_dpp v119, v58 row_ror:1 row_mask:0xf bank_mask:0xf
	v_mov_b32_dpp v122, v58 row_ror:2 row_mask:0xf bank_mask:0xf
	v_mov_b32_dpp v121, v59 row_ror:1 row_mask:0xf bank_mask:0xf
	v_mov_b32_dpp v123, v59 row_ror:2 row_mask:0xf bank_mask:0xf
	s_waitcnt vmcnt(0)
	s_and_saveexec_b64 s[46:47], s[0:1]
	s_cbranch_execz .LBB0_712
	v_cndmask_b32_e64 v130, v130, v122, s[8:9]
	v_cndmask_b32_e64 v131, v131, v123, s[8:9]
	v_cndmask_b32_e64 v102, v119, v102, s[6:7]
	v_cndmask_b32_e64 v103, v121, v103, s[6:7]
	v_pk_mul_f32 v[130:131], v[86:87], v[130:131]
	v_cndmask_b32_e64 v98, v106, v98, s[6:7]
	v_pk_fma_f32 v[102:103], v[90:91], v[102:103], v[130:131]
	v_cndmask_b32_e64 v99, v107, v99, s[6:7]
	v_pk_fma_f32 v[58:59], v[58:59], v[94:95], v[102:103]
	v_cndmask_b32_e64 v102, v126, v114, s[8:9]
	v_cndmask_b32_e64 v103, v127, v115, s[8:9]
	v_pk_mul_f32 v[102:103], v[78:79], v[102:103]
	v_cndmask_b32_e64 v128, v128, v118, s[8:9]
	v_pk_fma_f32 v[98:99], v[74:75], v[98:99], v[102:103]
	v_cndmask_b32_e64 v129, v129, v120, s[8:9]
	v_pk_fma_f32 v[62:63], v[62:63], v[82:83], v[98:99]
	v_cndmask_b32_e64 v100, v116, v100, s[6:7]
	v_mul_f32_e32 v98, 0xbfb8aa3b, v63
	v_exp_f32_e32 v98, v98
	v_cndmask_b32_e64 v101, v117, v101, s[6:7]
	v_pk_mul_f32 v[128:129], v[84:85], v[128:129]
	v_mul_f32_e32 v99, 0xbfb8aa3b, v62
	v_add_f32_e32 v98, 1.0, v98
	v_pk_fma_f32 v[100:101], v[88:89], v[100:101], v[128:129]
	v_rcp_f32_e32 v98, v98
	v_pk_fma_f32 v[56:57], v[56:57], v[92:93], v[100:101]
	v_cndmask_b32_e64 v100, v124, v112, s[8:9]
	v_cndmask_b32_e64 v101, v125, v113, s[8:9]
	v_exp_f32_e32 v99, v99
	v_pk_mul_f32 v[100:101], v[76:77], v[100:101]
	v_cndmask_b32_e64 v96, v104, v96, s[6:7]
	v_cndmask_b32_e64 v97, v105, v97, s[6:7]
	v_pk_fma_f32 v[96:97], v[72:73], v[96:97], v[100:101]
	v_mul_f32_e32 v63, v63, v98
	v_pk_fma_f32 v[60:61], v[60:61], v[80:81], v[96:97]
	v_mul_f32_e32 v59, v63, v59
	v_add_f32_e32 v63, 1.0, v99
	v_mul_f32_e32 v96, 0xbfb8aa3b, v61
	v_mul_f32_e32 v97, 0xbfb8aa3b, v60
	v_rcp_f32_e32 v63, v63
	v_exp_f32_e32 v96, v96
	v_exp_f32_e32 v97, v97
	v_mul_f32_e32 v62, v62, v63
	v_add_f32_e32 v63, 1.0, v96
	v_add_f32_e32 v96, 1.0, v97
	v_rcp_f32_e32 v63, v63
	v_rcp_f32_e32 v96, v96
	v_mul_f32_e32 v58, v62, v58
	v_mul_f32_e32 v61, v61, v63
	v_mul_f32_e32 v60, v60, v96
	v_mul_f32_e32 v57, v61, v57
	v_mul_f32_e32 v56, v60, v56
	v_cvt_pk_bf16_f32 v56, v56, v57
	v_cvt_pk_bf16_f32 v57, v58, v59
	v_mov_b64_e32 v[58:59], s[30:31]
	v_mad_i64_i32 v[58:59], s[0:1], v194, s67, v[58:59]
	v_lshl_add_u64 v[58:59], v[192:193], 1, v[58:59]
	global_store_dwordx2 v[58:59], v[56:57], off offset:8
.LBB0_712:
	s_or_b64 exec, exec, s[46:47]
	v_mov_b32_e32 v153, v152
	v_mov_b32_e32 v56, v152
	v_mov_b32_e32 v57, v152
	v_pk_fma_f32 v[54:55], v[54:55], v[56:57], v[46:47]
	v_pk_fma_f32 v[52:53], v[52:53], v[152:153], v[44:45]
	v_pk_fma_f32 v[50:51], v[50:51], v[56:57], v[42:43]
	v_pk_fma_f32 v[48:49], v[48:49], v[152:153], v[40:41]
	v_mov_b32_e32 v56, 0
	v_mov_b32_e32 v60, 0
	v_mov_b32_e32 v57, 0
	v_mov_b32_e32 v61, 0
	v_mov_b32_e32 v58, 0
	v_mov_b32_e32 v62, 0
	v_mov_b32_e32 v59, 0
	v_mov_b32_e32 v63, 0
	v_mov_b32_e32 v96, 0
	v_mov_b32_e32 v98, 0
	v_mov_b32_e32 v97, 0
	v_mov_b32_e32 v100, 0
	v_mov_b32_e32 v99, 0
	v_mov_b32_e32 v102, 0
	v_mov_b32_e32 v101, 0
	v_mov_b32_e32 v103, 0
	v_mov_b32_dpp v56, v52 row_ror:1 row_mask:0xf bank_mask:0xf
	v_mov_b32_dpp v60, v52 row_ror:2 row_mask:0xf bank_mask:0xf
	v_mov_b32_dpp v57, v53 row_ror:1 row_mask:0xf bank_mask:0xf
	v_mov_b32_dpp v61, v53 row_ror:2 row_mask:0xf bank_mask:0xf
	v_mov_b32_dpp v58, v54 row_ror:1 row_mask:0xf bank_mask:0xf
	v_mov_b32_dpp v62, v54 row_ror:2 row_mask:0xf bank_mask:0xf
	v_mov_b32_dpp v59, v55 row_ror:1 row_mask:0xf bank_mask:0xf
	v_mov_b32_dpp v63, v55 row_ror:2 row_mask:0xf bank_mask:0xf
	v_mov_b32_dpp v96, v48 row_ror:1 row_mask:0xf bank_mask:0xf
	v_mov_b32_dpp v98, v48 row_ror:2 row_mask:0xf bank_mask:0xf
	v_mov_b32_dpp v97, v49 row_ror:1 row_mask:0xf bank_mask:0xf
	v_mov_b32_dpp v100, v49 row_ror:2 row_mask:0xf bank_mask:0xf
	v_mov_b32_dpp v99, v50 row_ror:1 row_mask:0xf bank_mask:0xf
	v_mov_b32_dpp v102, v50 row_ror:2 row_mask:0xf bank_mask:0xf
	v_mov_b32_dpp v101, v51 row_ror:1 row_mask:0xf bank_mask:0xf
	v_mov_b32_dpp v103, v51 row_ror:2 row_mask:0xf bank_mask:0xf
	s_and_saveexec_b64 s[0:1], s[16:17]
	s_cbranch_execz .LBB0_714
	v_cndmask_b32_e64 v114, v114, v62, s[8:9]
	v_cndmask_b32_e64 v115, v115, v63, s[8:9]
	v_pk_mul_f32 v[114:115], v[78:79], v[114:115]
	v_cndmask_b32_e64 v106, v58, v106, s[6:7]
	v_cndmask_b32_e64 v107, v59, v107, s[6:7]
	v_pk_fma_f32 v[106:107], v[74:75], v[106:107], v[114:115]
	v_cndmask_b32_e64 v122, v122, v102, s[8:9]
	v_pk_fma_f32 v[54:55], v[54:55], v[82:83], v[106:107]
	v_cndmask_b32_e64 v123, v123, v103, s[8:9]
	v_mul_f32_e32 v106, 0xbfb8aa3b, v55
	v_exp_f32_e32 v106, v106
	v_mul_f32_e32 v107, 0xbfb8aa3b, v54
	v_cndmask_b32_e64 v112, v112, v60, s[8:9]
	v_cndmask_b32_e64 v113, v113, v61, s[8:9]
	v_add_f32_e32 v106, 1.0, v106
	v_rcp_f32_e32 v106, v106
	v_exp_f32_e32 v107, v107
	v_cndmask_b32_e64 v124, v118, v98, s[8:9]
	v_cndmask_b32_e64 v118, v99, v119, s[6:7]
	v_cndmask_b32_e64 v119, v101, v121, s[6:7]
	v_pk_mul_f32 v[122:123], v[86:87], v[122:123]
	v_pk_mul_f32 v[112:113], v[76:77], v[112:113]
	v_cndmask_b32_e64 v104, v56, v104, s[6:7]
	v_cndmask_b32_e64 v105, v57, v105, s[6:7]
	v_pk_fma_f32 v[118:119], v[90:91], v[118:119], v[122:123]
	v_pk_fma_f32 v[104:105], v[72:73], v[104:105], v[112:113]
	v_pk_fma_f32 v[50:51], v[50:51], v[94:95], v[118:119]
	v_pk_fma_f32 v[52:53], v[52:53], v[80:81], v[104:105]
	v_mul_f32_e32 v55, v55, v106
	v_mul_f32_e32 v51, v55, v51
	v_add_f32_e32 v55, 1.0, v107
	v_mul_f32_e32 v104, 0xbfb8aa3b, v53
	v_mul_f32_e32 v105, 0xbfb8aa3b, v52
	v_rcp_f32_e32 v55, v55
	v_exp_f32_e32 v104, v104
	v_exp_f32_e32 v105, v105
	v_cndmask_b32_e64 v125, v120, v100, s[8:9]
	v_mul_f32_e32 v54, v54, v55
	v_add_f32_e32 v55, 1.0, v104
	v_add_f32_e32 v104, 1.0, v105
	v_rcp_f32_e32 v55, v55
	v_rcp_f32_e32 v104, v104
	v_cndmask_b32_e64 v116, v96, v116, s[6:7]
	v_cndmask_b32_e64 v117, v97, v117, s[6:7]
	v_pk_mul_f32 v[120:121], v[84:85], v[124:125]
	v_mul_f32_e32 v53, v53, v55
	v_pk_fma_f32 v[116:117], v[88:89], v[116:117], v[120:121]
	v_mul_f32_e32 v52, v52, v104
	v_pk_fma_f32 v[48:49], v[48:49], v[92:93], v[116:117]
	v_mul_f32_e32 v50, v54, v50
	v_mul_f32_e32 v49, v53, v49
	v_mul_f32_e32 v48, v52, v48
	v_cvt_pk_bf16_f32 v48, v48, v49
	v_cvt_pk_bf16_f32 v49, v50, v51
	v_mov_b64_e32 v[50:51], s[30:31]
	v_mad_i64_i32 v[50:51], s[16:17], v154, s67, v[50:51]
	v_lshl_add_u64 v[50:51], v[192:193], 1, v[50:51]
	global_store_dwordx2 v[50:51], v[48:49], off offset:8
.LBB0_714:
	s_or_b64 exec, exec, s[0:1]
	v_mov_b32_e32 v145, v144
	v_mov_b32_e32 v48, v144
	v_mov_b32_e32 v49, v144
	v_pk_fma_f32 v[34:35], v[34:35], v[48:49], v[46:47]
	v_pk_fma_f32 v[32:33], v[32:33], v[144:145], v[44:45]
	v_pk_fma_f32 v[30:31], v[30:31], v[48:49], v[42:43]
	v_pk_fma_f32 v[28:29], v[28:29], v[144:145], v[40:41]
	v_mov_b32_e32 v48, 0
	v_mov_b32_e32 v52, 0
	v_mov_b32_e32 v49, 0
	v_mov_b32_e32 v53, 0
	v_mov_b32_e32 v50, 0
	v_mov_b32_e32 v54, 0
	v_mov_b32_e32 v51, 0
	v_mov_b32_e32 v55, 0
	v_mov_b32_e32 v104, 0
	v_mov_b32_e32 v106, 0
	v_mov_b32_e32 v105, 0
	v_mov_b32_e32 v112, 0
	v_mov_b32_e32 v107, 0
	v_mov_b32_e32 v114, 0
	v_mov_b32_e32 v113, 0
	v_mov_b32_e32 v115, 0
	v_mov_b32_dpp v48, v32 row_ror:1 row_mask:0xf bank_mask:0xf
	v_mov_b32_dpp v52, v32 row_ror:2 row_mask:0xf bank_mask:0xf
	v_mov_b32_dpp v49, v33 row_ror:1 row_mask:0xf bank_mask:0xf
	v_mov_b32_dpp v53, v33 row_ror:2 row_mask:0xf bank_mask:0xf
	v_mov_b32_dpp v50, v34 row_ror:1 row_mask:0xf bank_mask:0xf
	v_mov_b32_dpp v54, v34 row_ror:2 row_mask:0xf bank_mask:0xf
	v_mov_b32_dpp v51, v35 row_ror:1 row_mask:0xf bank_mask:0xf
	v_mov_b32_dpp v55, v35 row_ror:2 row_mask:0xf bank_mask:0xf
	v_mov_b32_dpp v104, v28 row_ror:1 row_mask:0xf bank_mask:0xf
	v_mov_b32_dpp v106, v28 row_ror:2 row_mask:0xf bank_mask:0xf
	v_mov_b32_dpp v105, v29 row_ror:1 row_mask:0xf bank_mask:0xf
	v_mov_b32_dpp v112, v29 row_ror:2 row_mask:0xf bank_mask:0xf
	v_mov_b32_dpp v107, v30 row_ror:1 row_mask:0xf bank_mask:0xf
	v_mov_b32_dpp v114, v30 row_ror:2 row_mask:0xf bank_mask:0xf
	v_mov_b32_dpp v113, v31 row_ror:1 row_mask:0xf bank_mask:0xf
	v_mov_b32_dpp v115, v31 row_ror:2 row_mask:0xf bank_mask:0xf
	s_and_saveexec_b64 s[0:1], s[18:19]
	s_cbranch_execz .LBB0_716
	v_cndmask_b32_e64 v62, v62, v54, s[8:9]
	v_cndmask_b32_e64 v63, v63, v55, s[8:9]
	v_pk_mul_f32 v[62:63], v[78:79], v[62:63]
	v_cndmask_b32_e64 v58, v50, v58, s[6:7]
	v_cndmask_b32_e64 v59, v51, v59, s[6:7]
	v_pk_fma_f32 v[58:59], v[74:75], v[58:59], v[62:63]
	v_cndmask_b32_e64 v102, v102, v114, s[8:9]
	v_pk_fma_f32 v[34:35], v[34:35], v[82:83], v[58:59]
	v_cndmask_b32_e64 v103, v103, v115, s[8:9]
	v_mul_f32_e32 v58, 0xbfb8aa3b, v35
	v_exp_f32_e32 v58, v58
	v_mul_f32_e32 v59, 0xbfb8aa3b, v34
	v_cndmask_b32_e64 v60, v60, v52, s[8:9]
	v_cndmask_b32_e64 v61, v61, v53, s[8:9]
	v_add_f32_e32 v58, 1.0, v58
	v_rcp_f32_e32 v58, v58
	v_exp_f32_e32 v59, v59
	v_cndmask_b32_e64 v116, v98, v106, s[8:9]
	v_cndmask_b32_e64 v98, v107, v99, s[6:7]
	v_cndmask_b32_e64 v99, v113, v101, s[6:7]
	v_pk_mul_f32 v[102:103], v[86:87], v[102:103]
	v_pk_mul_f32 v[60:61], v[76:77], v[60:61]
	v_cndmask_b32_e64 v56, v48, v56, s[6:7]
	v_cndmask_b32_e64 v57, v49, v57, s[6:7]
	v_pk_fma_f32 v[98:99], v[90:91], v[98:99], v[102:103]
	v_pk_fma_f32 v[56:57], v[72:73], v[56:57], v[60:61]
	v_pk_fma_f32 v[30:31], v[30:31], v[94:95], v[98:99]
	v_pk_fma_f32 v[32:33], v[32:33], v[80:81], v[56:57]
	v_mul_f32_e32 v35, v35, v58
	v_mul_f32_e32 v31, v35, v31
	v_add_f32_e32 v35, 1.0, v59
	v_mul_f32_e32 v56, 0xbfb8aa3b, v33
	v_mul_f32_e32 v57, 0xbfb8aa3b, v32
	v_rcp_f32_e32 v35, v35
	v_exp_f32_e32 v56, v56
	v_exp_f32_e32 v57, v57
	v_cndmask_b32_e64 v117, v100, v112, s[8:9]
	v_mul_f32_e32 v34, v34, v35
	v_add_f32_e32 v35, 1.0, v56
	v_add_f32_e32 v56, 1.0, v57
	v_rcp_f32_e32 v35, v35
	v_rcp_f32_e32 v56, v56
	v_cndmask_b32_e64 v96, v104, v96, s[6:7]
	v_cndmask_b32_e64 v97, v105, v97, s[6:7]
	v_pk_mul_f32 v[100:101], v[84:85], v[116:117]
	v_mul_f32_e32 v33, v33, v35
	v_pk_fma_f32 v[96:97], v[88:89], v[96:97], v[100:101]
	v_mul_f32_e32 v32, v32, v56
	v_pk_fma_f32 v[28:29], v[28:29], v[92:93], v[96:97]
	v_mul_f32_e32 v30, v34, v30
	v_mul_f32_e32 v29, v33, v29
	v_mul_f32_e32 v28, v32, v28
	v_cvt_pk_bf16_f32 v28, v28, v29
	v_cvt_pk_bf16_f32 v29, v30, v31
	v_mov_b64_e32 v[30:31], s[30:31]
	v_mad_i64_i32 v[30:31], s[16:17], v147, s67, v[30:31]
	v_lshl_add_u64 v[30:31], v[192:193], 1, v[30:31]
	global_store_dwordx2 v[30:31], v[28:29], off offset:8
.LBB0_716:
	s_or_b64 exec, exec, s[0:1]
	v_mov_b32_e32 v28, 0
	v_mov_b32_e32 v32, 0
	v_mov_b32_e32 v29, 0
	v_mov_b32_e32 v33, 0
	v_mov_b32_e32 v30, 0
	v_mov_b32_e32 v34, 0
	v_mov_b32_e32 v31, 0
	v_mov_b32_e32 v35, 0
	v_mov_b32_e32 v56, 0
	v_mov_b32_e32 v58, 0
	v_mov_b32_e32 v57, 0
	v_mov_b32_e32 v60, 0
	v_mov_b32_e32 v59, 0
	v_mov_b32_e32 v62, 0
	v_mov_b32_e32 v61, 0
	v_mov_b32_e32 v63, 0
	v_mov_b32_dpp v28, v64 row_ror:1 row_mask:0xf bank_mask:0xf
	v_mov_b32_dpp v32, v64 row_ror:2 row_mask:0xf bank_mask:0xf
	v_mov_b32_dpp v29, v65 row_ror:1 row_mask:0xf bank_mask:0xf
	v_mov_b32_dpp v33, v65 row_ror:2 row_mask:0xf bank_mask:0xf
	v_mov_b32_dpp v30, v66 row_ror:1 row_mask:0xf bank_mask:0xf
	v_mov_b32_dpp v34, v66 row_ror:2 row_mask:0xf bank_mask:0xf
	v_mov_b32_dpp v31, v67 row_ror:1 row_mask:0xf bank_mask:0xf
	v_mov_b32_dpp v35, v67 row_ror:2 row_mask:0xf bank_mask:0xf
	v_mov_b32_dpp v56, v68 row_ror:1 row_mask:0xf bank_mask:0xf
	v_mov_b32_dpp v58, v68 row_ror:2 row_mask:0xf bank_mask:0xf
	v_mov_b32_dpp v57, v69 row_ror:1 row_mask:0xf bank_mask:0xf
	v_mov_b32_dpp v60, v69 row_ror:2 row_mask:0xf bank_mask:0xf
	v_mov_b32_dpp v59, v70 row_ror:1 row_mask:0xf bank_mask:0xf
	v_mov_b32_dpp v62, v70 row_ror:2 row_mask:0xf bank_mask:0xf
	v_mov_b32_dpp v61, v71 row_ror:1 row_mask:0xf bank_mask:0xf
	v_mov_b32_dpp v63, v71 row_ror:2 row_mask:0xf bank_mask:0xf
	s_and_saveexec_b64 s[0:1], s[20:21]
	s_cbranch_execz .LBB0_718
	v_cndmask_b32_e64 v34, v54, v34, s[8:9]
	v_cndmask_b32_e64 v35, v55, v35, s[8:9]
	v_pk_mul_f32 v[34:35], v[78:79], v[34:35]
	v_cndmask_b32_e64 v30, v30, v50, s[6:7]
	v_cndmask_b32_e64 v31, v31, v51, s[6:7]
	v_pk_fma_f32 v[30:31], v[74:75], v[30:31], v[34:35]
	v_cndmask_b32_e64 v32, v52, v32, s[8:9]
	v_pk_fma_f32 v[30:31], v[66:67], v[82:83], v[30:31]
	v_cndmask_b32_e64 v33, v53, v33, s[8:9]
	v_mul_f32_e32 v34, 0xbfb8aa3b, v31
	v_exp_f32_e32 v34, v34
	v_pk_mul_f32 v[32:33], v[76:77], v[32:33]
	v_cndmask_b32_e64 v28, v28, v48, s[6:7]
	v_cndmask_b32_e64 v29, v29, v49, s[6:7]
	v_pk_fma_f32 v[28:29], v[72:73], v[28:29], v[32:33]
	v_add_f32_e32 v32, 1.0, v34
	v_mul_f32_e32 v33, 0xbfb8aa3b, v30
	v_rcp_f32_e32 v32, v32
	v_exp_f32_e32 v33, v33
	v_pk_fma_f32 v[28:29], v[64:65], v[80:81], v[28:29]
	v_cndmask_b32_e64 v96, v106, v58, s[8:9]
	v_mul_f32_e32 v31, v31, v32
	v_add_f32_e32 v32, 1.0, v33
	v_mul_f32_e32 v33, 0xbfb8aa3b, v29
	v_mul_f32_e32 v34, 0xbfb8aa3b, v28
	v_rcp_f32_e32 v32, v32
	v_exp_f32_e32 v33, v33
	v_exp_f32_e32 v34, v34
	v_cndmask_b32_e64 v97, v112, v60, s[8:9]
	v_mul_f32_e32 v30, v30, v32
	v_add_f32_e32 v32, 1.0, v33
	v_add_f32_e32 v33, 1.0, v34
	v_rcp_f32_e32 v32, v32
	v_rcp_f32_e32 v33, v33
	v_cndmask_b32_e64 v62, v114, v62, s[8:9]
	v_cndmask_b32_e64 v63, v115, v63, s[8:9]
	v_cndmask_b32_e64 v56, v56, v104, s[6:7]
	v_cndmask_b32_e64 v57, v57, v105, s[6:7]
	v_cndmask_b32_e64 v58, v59, v107, s[6:7]
	v_cndmask_b32_e64 v59, v61, v113, s[6:7]
	v_pk_mul_f32 v[60:61], v[84:85], v[96:97]
	v_pk_mul_f32 v[62:63], v[86:87], v[62:63]
	v_pk_fma_f32 v[56:57], v[88:89], v[56:57], v[60:61]
	v_pk_fma_f32 v[58:59], v[90:91], v[58:59], v[62:63]
	v_pk_fma_f32 v[56:57], v[68:69], v[92:93], v[56:57]
	v_pk_fma_f32 v[58:59], v[70:71], v[94:95], v[58:59]
	v_mul_f32_e32 v29, v29, v32
	v_mul_f32_e32 v28, v28, v33
	v_mul_f32_e32 v31, v31, v59
	v_mul_f32_e32 v30, v30, v58
	v_mul_f32_e32 v29, v29, v57
	v_mul_f32_e32 v28, v28, v56
	v_cvt_pk_bf16_f32 v28, v28, v29
	v_cvt_pk_bf16_f32 v29, v30, v31
	v_mov_b64_e32 v[30:31], s[30:31]
	v_mad_i64_i32 v[30:31], s[16:17], v109, s67, v[30:31]
	v_lshl_add_u64 v[30:31], v[192:193], 1, v[30:31]
	global_store_dwordx2 v[30:31], v[28:29], off offset:8
.LBB0_718:
	s_or_b64 exec, exec, s[0:1]
	v_mov_b32_e32 v109, v108
	v_mov_b32_e32 v28, v108
	v_mov_b32_e32 v29, v108
	v_pk_fma_f32 v[22:23], v[22:23], v[28:29], v[46:47]
	v_pk_fma_f32 v[20:21], v[20:21], v[108:109], v[44:45]
	v_pk_fma_f32 v[18:19], v[18:19], v[28:29], v[42:43]
	v_pk_fma_f32 v[16:17], v[16:17], v[108:109], v[40:41]
	v_mov_b32_e32 v28, 0
	v_mov_b32_e32 v32, 0
	v_mov_b32_e32 v29, 0
	v_mov_b32_e32 v33, 0
	v_mov_b32_e32 v30, 0
	v_mov_b32_e32 v34, 0
	v_mov_b32_e32 v31, 0
	v_mov_b32_e32 v35, 0
	v_mov_b32_e32 v48, 0
	v_mov_b32_e32 v50, 0
	v_mov_b32_e32 v49, 0
	v_mov_b32_e32 v52, 0
	v_mov_b32_e32 v51, 0
	v_mov_b32_e32 v54, 0
	v_mov_b32_e32 v53, 0
	v_mov_b32_e32 v55, 0
	v_mov_b32_dpp v28, v20 row_ror:1 row_mask:0xf bank_mask:0xf
	v_mov_b32_dpp v32, v20 row_ror:2 row_mask:0xf bank_mask:0xf
	v_mov_b32_dpp v29, v21 row_ror:1 row_mask:0xf bank_mask:0xf
	v_mov_b32_dpp v33, v21 row_ror:2 row_mask:0xf bank_mask:0xf
	v_mov_b32_dpp v30, v22 row_ror:1 row_mask:0xf bank_mask:0xf
	v_mov_b32_dpp v34, v22 row_ror:2 row_mask:0xf bank_mask:0xf
	v_mov_b32_dpp v31, v23 row_ror:1 row_mask:0xf bank_mask:0xf
	v_mov_b32_dpp v35, v23 row_ror:2 row_mask:0xf bank_mask:0xf
	v_mov_b32_dpp v48, v16 row_ror:1 row_mask:0xf bank_mask:0xf
	v_mov_b32_dpp v50, v16 row_ror:2 row_mask:0xf bank_mask:0xf
	v_mov_b32_dpp v49, v17 row_ror:1 row_mask:0xf bank_mask:0xf
	v_mov_b32_dpp v52, v17 row_ror:2 row_mask:0xf bank_mask:0xf
	v_mov_b32_dpp v51, v18 row_ror:1 row_mask:0xf bank_mask:0xf
	v_mov_b32_dpp v54, v18 row_ror:2 row_mask:0xf bank_mask:0xf
	v_mov_b32_dpp v53, v19 row_ror:1 row_mask:0xf bank_mask:0xf
	v_mov_b32_dpp v55, v19 row_ror:2 row_mask:0xf bank_mask:0xf
	s_and_saveexec_b64 s[0:1], s[22:23]
	s_cbranch_execz .LBB0_720
	ds_read_b128 v[56:59], v149 offset:304
	ds_read_b128 v[60:63], v149 offset:48
	ds_read_b128 v[64:67], v149 offset:16
	ds_read_b128 v[68:71], v149 offset:272
	s_waitcnt lgkmcnt(2)
	v_cndmask_b32_e64 v63, v59, v63, s[6:7]
	v_cndmask_b32_e64 v62, v58, v62, s[6:7]
	v_cndmask_b32_e64 v62, v62, v54, s[8:9]
	v_cndmask_b32_e64 v63, v63, v55, s[8:9]
	v_cndmask_b32_e64 v58, v51, v58, s[6:7]
	v_cndmask_b32_e64 v59, v53, v59, s[6:7]
	v_pk_mul_f32 v[62:63], v[86:87], v[62:63]
	v_cndmask_b32_e64 v61, v57, v61, s[6:7]
	v_cndmask_b32_e64 v60, v56, v60, s[6:7]
	v_pk_fma_f32 v[58:59], v[90:91], v[58:59], v[62:63]
	v_cndmask_b32_e64 v60, v60, v50, s[8:9]
	v_cndmask_b32_e64 v61, v61, v52, s[8:9]
	v_pk_fma_f32 v[18:19], v[18:19], v[94:95], v[58:59]
	s_waitcnt lgkmcnt(0)
	v_cndmask_b32_e64 v59, v71, v67, s[6:7]
	v_cndmask_b32_e64 v58, v70, v66, s[6:7]
	v_cndmask_b32_e64 v56, v48, v56, s[6:7]
	v_cndmask_b32_e64 v57, v49, v57, s[6:7]
	v_pk_mul_f32 v[60:61], v[84:85], v[60:61]
	v_cndmask_b32_e64 v58, v58, v34, s[8:9]
	v_cndmask_b32_e64 v59, v59, v35, s[8:9]
	v_pk_fma_f32 v[56:57], v[88:89], v[56:57], v[60:61]
	v_pk_mul_f32 v[58:59], v[78:79], v[58:59]
	v_cndmask_b32_e64 v60, v30, v70, s[6:7]
	v_cndmask_b32_e64 v61, v31, v71, s[6:7]
	v_pk_fma_f32 v[58:59], v[74:75], v[60:61], v[58:59]
	v_pk_fma_f32 v[16:17], v[16:17], v[92:93], v[56:57]
	v_pk_fma_f32 v[22:23], v[22:23], v[82:83], v[58:59]
	v_cndmask_b32_e64 v57, v69, v65, s[6:7]
	v_mul_f32_e32 v58, 0xbfb8aa3b, v23
	v_exp_f32_e32 v60, v58
	v_cndmask_b32_e64 v56, v68, v64, s[6:7]
	v_cndmask_b32_e64 v56, v56, v32, s[8:9]
	v_cndmask_b32_e64 v57, v57, v33, s[8:9]
	v_pk_mul_f32 v[56:57], v[76:77], v[56:57]
	v_cndmask_b32_e64 v58, v28, v68, s[6:7]
	v_cndmask_b32_e64 v59, v29, v69, s[6:7]
	v_pk_fma_f32 v[56:57], v[72:73], v[58:59], v[56:57]
	v_add_f32_e32 v58, 1.0, v60
	v_rcp_f32_e32 v58, v58
	v_mul_f32_e32 v59, 0xbfb8aa3b, v22
	v_exp_f32_e32 v59, v59
	v_pk_fma_f32 v[20:21], v[20:21], v[80:81], v[56:57]
	v_mul_f32_e32 v23, v23, v58
	v_mul_f32_e32 v19, v19, v23
	v_add_f32_e32 v23, 1.0, v59
	v_mul_f32_e32 v56, 0xbfb8aa3b, v21
	v_mul_f32_e32 v57, 0xbfb8aa3b, v20
	v_rcp_f32_e32 v23, v23
	v_exp_f32_e32 v56, v56
	v_exp_f32_e32 v57, v57
	v_mul_f32_e32 v22, v22, v23
	v_add_f32_e32 v23, 1.0, v56
	v_add_f32_e32 v56, 1.0, v57
	v_rcp_f32_e32 v23, v23
	v_rcp_f32_e32 v56, v56
	v_mul_f32_e32 v18, v18, v22
	v_mul_f32_e32 v21, v21, v23
	v_mul_f32_e32 v20, v20, v56
	v_mul_f32_e32 v17, v17, v21
	v_mul_f32_e32 v16, v16, v20
	v_cvt_pk_bf16_f32 v16, v16, v17
	v_cvt_pk_bf16_f32 v17, v18, v19
	v_mov_b64_e32 v[18:19], s[30:31]
	v_mad_i64_i32 v[18:19], s[16:17], v111, s67, v[18:19]
	v_lshl_add_u64 v[18:19], v[192:193], 1, v[18:19]
	global_store_dwordx2 v[18:19], v[16:17], off offset:8
.LBB0_720:
	s_or_b64 exec, exec, s[0:1]
	v_mov_b32_e32 v147, v146
	v_mov_b32_e32 v16, v146
	v_mov_b32_e32 v17, v146
	v_pk_fma_f32 v[14:15], v[14:15], v[16:17], v[46:47]
	v_pk_fma_f32 v[12:13], v[12:13], v[146:147], v[44:45]
	v_pk_fma_f32 v[10:11], v[10:11], v[16:17], v[42:43]
	v_pk_fma_f32 v[8:9], v[8:9], v[146:147], v[40:41]
	v_mov_b32_e32 v16, 0
	v_mov_b32_e32 v20, 0
	v_mov_b32_e32 v17, 0
	v_mov_b32_e32 v21, 0
	v_mov_b32_e32 v18, 0
	v_mov_b32_e32 v22, 0
	v_mov_b32_e32 v19, 0
	v_mov_b32_e32 v23, 0
	v_mov_b32_e32 v56, 0
	v_mov_b32_e32 v58, 0
	v_mov_b32_e32 v57, 0
	v_mov_b32_e32 v60, 0
	v_mov_b32_e32 v59, 0
	v_mov_b32_e32 v62, 0
	v_mov_b32_e32 v61, 0
	v_mov_b32_e32 v63, 0
	v_mov_b32_dpp v16, v12 row_ror:1 row_mask:0xf bank_mask:0xf
	v_mov_b32_dpp v20, v12 row_ror:2 row_mask:0xf bank_mask:0xf
	v_mov_b32_dpp v17, v13 row_ror:1 row_mask:0xf bank_mask:0xf
	v_mov_b32_dpp v21, v13 row_ror:2 row_mask:0xf bank_mask:0xf
	v_mov_b32_dpp v18, v14 row_ror:1 row_mask:0xf bank_mask:0xf
	v_mov_b32_dpp v22, v14 row_ror:2 row_mask:0xf bank_mask:0xf
	v_mov_b32_dpp v19, v15 row_ror:1 row_mask:0xf bank_mask:0xf
	v_mov_b32_dpp v23, v15 row_ror:2 row_mask:0xf bank_mask:0xf
	v_mov_b32_dpp v56, v8 row_ror:1 row_mask:0xf bank_mask:0xf
	v_mov_b32_dpp v58, v8 row_ror:2 row_mask:0xf bank_mask:0xf
	v_mov_b32_dpp v57, v9 row_ror:1 row_mask:0xf bank_mask:0xf
	v_mov_b32_dpp v60, v9 row_ror:2 row_mask:0xf bank_mask:0xf
	v_mov_b32_dpp v59, v10 row_ror:1 row_mask:0xf bank_mask:0xf
	v_mov_b32_dpp v62, v10 row_ror:2 row_mask:0xf bank_mask:0xf
	v_mov_b32_dpp v61, v11 row_ror:1 row_mask:0xf bank_mask:0xf
	v_mov_b32_dpp v63, v11 row_ror:2 row_mask:0xf bank_mask:0xf
	s_and_saveexec_b64 s[0:1], s[24:25]
	s_cbranch_execz .LBB0_722
	v_cndmask_b32_e64 v34, v34, v22, s[8:9]
	v_cndmask_b32_e64 v35, v35, v23, s[8:9]
	v_pk_mul_f32 v[34:35], v[78:79], v[34:35]
	v_cndmask_b32_e64 v30, v18, v30, s[6:7]
	v_cndmask_b32_e64 v31, v19, v31, s[6:7]
	v_pk_fma_f32 v[30:31], v[74:75], v[30:31], v[34:35]
	v_cndmask_b32_e64 v54, v54, v62, s[8:9]
	v_pk_fma_f32 v[14:15], v[14:15], v[82:83], v[30:31]
	v_cndmask_b32_e64 v55, v55, v63, s[8:9]
	v_mul_f32_e32 v30, 0xbfb8aa3b, v15
	v_exp_f32_e32 v30, v30
	v_mul_f32_e32 v31, 0xbfb8aa3b, v14
	v_cndmask_b32_e64 v32, v32, v20, s[8:9]
	v_cndmask_b32_e64 v33, v33, v21, s[8:9]
	v_add_f32_e32 v30, 1.0, v30
	v_rcp_f32_e32 v30, v30
	v_exp_f32_e32 v31, v31
	v_cndmask_b32_e64 v64, v50, v58, s[8:9]
	v_cndmask_b32_e64 v50, v59, v51, s[6:7]
	v_cndmask_b32_e64 v51, v61, v53, s[6:7]
	v_pk_mul_f32 v[54:55], v[86:87], v[54:55]
	v_pk_mul_f32 v[32:33], v[76:77], v[32:33]
	v_cndmask_b32_e64 v28, v16, v28, s[6:7]
	v_cndmask_b32_e64 v29, v17, v29, s[6:7]
	v_pk_fma_f32 v[50:51], v[90:91], v[50:51], v[54:55]
	v_pk_fma_f32 v[28:29], v[72:73], v[28:29], v[32:33]
	v_pk_fma_f32 v[10:11], v[10:11], v[94:95], v[50:51]
	v_pk_fma_f32 v[12:13], v[12:13], v[80:81], v[28:29]
	v_mul_f32_e32 v15, v15, v30
	v_mul_f32_e32 v11, v15, v11
	v_add_f32_e32 v15, 1.0, v31
	v_mul_f32_e32 v28, 0xbfb8aa3b, v13
	v_mul_f32_e32 v29, 0xbfb8aa3b, v12
	v_rcp_f32_e32 v15, v15
	v_exp_f32_e32 v28, v28
	v_exp_f32_e32 v29, v29
	v_cndmask_b32_e64 v65, v52, v60, s[8:9]
	v_mul_f32_e32 v14, v14, v15
	v_add_f32_e32 v15, 1.0, v28
	v_add_f32_e32 v28, 1.0, v29
	v_rcp_f32_e32 v15, v15
	v_rcp_f32_e32 v28, v28
	v_cndmask_b32_e64 v48, v56, v48, s[6:7]
	v_cndmask_b32_e64 v49, v57, v49, s[6:7]
	v_pk_mul_f32 v[52:53], v[84:85], v[64:65]
	v_mul_f32_e32 v13, v13, v15
	v_pk_fma_f32 v[48:49], v[88:89], v[48:49], v[52:53]
	v_mul_f32_e32 v12, v12, v28
	v_pk_fma_f32 v[8:9], v[8:9], v[92:93], v[48:49]
	v_mul_f32_e32 v10, v14, v10
	v_mul_f32_e32 v9, v13, v9
	v_mul_f32_e32 v8, v12, v8
	v_cvt_pk_bf16_f32 v8, v8, v9
	v_cvt_pk_bf16_f32 v9, v10, v11
	v_mov_b64_e32 v[10:11], s[30:31]
	v_mad_i64_i32 v[10:11], s[16:17], v148, s67, v[10:11]
	v_lshl_add_u64 v[10:11], v[192:193], 1, v[10:11]
	global_store_dwordx2 v[10:11], v[8:9], off offset:8
.LBB0_722:
	s_or_b64 exec, exec, s[0:1]
	v_mov_b32_e32 v111, v110
	v_mov_b32_e32 v8, v110
	v_mov_b32_e32 v9, v110
	v_pk_fma_f32 v[6:7], v[6:7], v[8:9], v[46:47]
	v_pk_fma_f32 v[4:5], v[4:5], v[110:111], v[44:45]
	v_pk_fma_f32 v[2:3], v[2:3], v[8:9], v[42:43]
	v_pk_fma_f32 v[0:1], v[0:1], v[110:111], v[40:41]
	v_mov_b32_e32 v8, 0
	v_mov_b32_e32 v12, 0
	v_mov_b32_e32 v9, 0
	v_mov_b32_e32 v13, 0
	v_mov_b32_e32 v10, 0
	v_mov_b32_e32 v14, 0
	v_mov_b32_e32 v11, 0
	v_mov_b32_e32 v15, 0
	v_mov_b32_e32 v28, 0
	v_mov_b32_e32 v32, 0
	v_mov_b32_e32 v29, 0
	v_mov_b32_e32 v33, 0
	v_mov_b32_e32 v30, 0
	v_mov_b32_e32 v34, 0
	v_mov_b32_e32 v31, 0
	v_mov_b32_e32 v35, 0
	v_mov_b32_dpp v8, v4 row_ror:1 row_mask:0xf bank_mask:0xf
	v_mov_b32_dpp v12, v4 row_ror:2 row_mask:0xf bank_mask:0xf
	v_mov_b32_dpp v9, v5 row_ror:1 row_mask:0xf bank_mask:0xf
	v_mov_b32_dpp v13, v5 row_ror:2 row_mask:0xf bank_mask:0xf
	v_mov_b32_dpp v10, v6 row_ror:1 row_mask:0xf bank_mask:0xf
	v_mov_b32_dpp v14, v6 row_ror:2 row_mask:0xf bank_mask:0xf
	v_mov_b32_dpp v11, v7 row_ror:1 row_mask:0xf bank_mask:0xf
	v_mov_b32_dpp v15, v7 row_ror:2 row_mask:0xf bank_mask:0xf
	v_mov_b32_dpp v28, v0 row_ror:1 row_mask:0xf bank_mask:0xf
	v_mov_b32_dpp v32, v0 row_ror:2 row_mask:0xf bank_mask:0xf
	v_mov_b32_dpp v29, v1 row_ror:1 row_mask:0xf bank_mask:0xf
	v_mov_b32_dpp v33, v1 row_ror:2 row_mask:0xf bank_mask:0xf
	v_mov_b32_dpp v30, v2 row_ror:1 row_mask:0xf bank_mask:0xf
	v_mov_b32_dpp v34, v2 row_ror:2 row_mask:0xf bank_mask:0xf
	v_mov_b32_dpp v31, v3 row_ror:1 row_mask:0xf bank_mask:0xf
	v_mov_b32_dpp v35, v3 row_ror:2 row_mask:0xf bank_mask:0xf
	s_and_saveexec_b64 s[0:1], s[26:27]
	s_cbranch_execz .LBB0_724
	v_cndmask_b32_e64 v22, v22, v14, s[8:9]
	v_cndmask_b32_e64 v23, v23, v15, s[8:9]
	v_pk_mul_f32 v[22:23], v[78:79], v[22:23]
	v_cndmask_b32_e64 v18, v10, v18, s[6:7]
	v_cndmask_b32_e64 v19, v11, v19, s[6:7]
	v_pk_fma_f32 v[18:19], v[74:75], v[18:19], v[22:23]
	v_cndmask_b32_e64 v42, v62, v34, s[8:9]
	v_pk_fma_f32 v[6:7], v[6:7], v[82:83], v[18:19]
	v_cndmask_b32_e64 v43, v63, v35, s[8:9]
	v_mul_f32_e32 v18, 0xbfb8aa3b, v7
	v_exp_f32_e32 v18, v18
	v_mul_f32_e32 v19, 0xbfb8aa3b, v6
	v_cndmask_b32_e64 v20, v20, v12, s[8:9]
	v_cndmask_b32_e64 v21, v21, v13, s[8:9]
	v_add_f32_e32 v18, 1.0, v18
	v_rcp_f32_e32 v18, v18
	v_exp_f32_e32 v19, v19
	v_cndmask_b32_e64 v46, v30, v59, s[6:7]
	v_cndmask_b32_e64 v47, v31, v61, s[6:7]
	v_pk_mul_f32 v[42:43], v[86:87], v[42:43]
	v_pk_mul_f32 v[20:21], v[76:77], v[20:21]
	v_cndmask_b32_e64 v16, v8, v16, s[6:7]
	v_cndmask_b32_e64 v17, v9, v17, s[6:7]
	v_pk_fma_f32 v[42:43], v[90:91], v[46:47], v[42:43]
	v_pk_fma_f32 v[16:17], v[72:73], v[16:17], v[20:21]
	v_pk_fma_f32 v[2:3], v[2:3], v[94:95], v[42:43]
	v_pk_fma_f32 v[4:5], v[4:5], v[80:81], v[16:17]
	v_mul_f32_e32 v7, v7, v18
	v_mul_f32_e32 v3, v7, v3
	v_add_f32_e32 v7, 1.0, v19
	v_mul_f32_e32 v16, 0xbfb8aa3b, v5
	v_mul_f32_e32 v17, 0xbfb8aa3b, v4
	v_rcp_f32_e32 v7, v7
	v_exp_f32_e32 v16, v16
	v_exp_f32_e32 v17, v17
	v_cndmask_b32_e64 v40, v58, v32, s[8:9]
	v_mul_f32_e32 v6, v6, v7
	v_add_f32_e32 v7, 1.0, v16
	v_add_f32_e32 v16, 1.0, v17
	v_rcp_f32_e32 v7, v7
	v_rcp_f32_e32 v16, v16
	v_cndmask_b32_e64 v41, v60, v33, s[8:9]
	v_cndmask_b32_e64 v44, v28, v56, s[6:7]
	v_cndmask_b32_e64 v45, v29, v57, s[6:7]
	v_pk_mul_f32 v[40:41], v[84:85], v[40:41]
	v_mul_f32_e32 v5, v5, v7
	v_pk_fma_f32 v[40:41], v[88:89], v[44:45], v[40:41]
	v_mul_f32_e32 v4, v4, v16
	v_pk_fma_f32 v[0:1], v[0:1], v[92:93], v[40:41]
	v_mul_f32_e32 v2, v6, v2
	v_mul_f32_e32 v1, v5, v1
	v_mul_f32_e32 v0, v4, v0
	v_cvt_pk_bf16_f32 v0, v0, v1
	v_cvt_pk_bf16_f32 v1, v2, v3
	v_mov_b64_e32 v[2:3], s[30:31]
	v_mad_i64_i32 v[2:3], s[16:17], v136, s67, v[2:3]
	v_lshl_add_u64 v[2:3], v[192:193], 1, v[2:3]
	global_store_dwordx2 v[2:3], v[0:1], off offset:8
.LBB0_724:
	s_or_b64 exec, exec, s[0:1]
	v_mov_b32_e32 v0, 0
	v_mov_b32_e32 v4, 0
	v_mov_b32_e32 v1, 0
	v_mov_b32_e32 v5, 0
	v_mov_b32_e32 v2, 0
	v_mov_b32_e32 v6, 0
	v_mov_b32_e32 v3, 0
	v_mov_b32_e32 v7, 0
	v_mov_b32_e32 v16, 0
	v_mov_b32_e32 v20, 0
	v_mov_b32_e32 v17, 0
	v_mov_b32_e32 v21, 0
	v_mov_b32_e32 v18, 0
	v_mov_b32_e32 v22, 0
	v_mov_b32_e32 v19, 0
	v_mov_b32_e32 v23, 0
	v_mov_b32_dpp v0, v24 row_ror:1 row_mask:0xf bank_mask:0xf
	v_mov_b32_dpp v4, v24 row_ror:2 row_mask:0xf bank_mask:0xf
	v_mov_b32_dpp v1, v25 row_ror:1 row_mask:0xf bank_mask:0xf
	v_mov_b32_dpp v5, v25 row_ror:2 row_mask:0xf bank_mask:0xf
	v_mov_b32_dpp v2, v26 row_ror:1 row_mask:0xf bank_mask:0xf
	v_mov_b32_dpp v6, v26 row_ror:2 row_mask:0xf bank_mask:0xf
	v_mov_b32_dpp v3, v27 row_ror:1 row_mask:0xf bank_mask:0xf
	v_mov_b32_dpp v7, v27 row_ror:2 row_mask:0xf bank_mask:0xf
	v_mov_b32_dpp v16, v36 row_ror:1 row_mask:0xf bank_mask:0xf
	v_mov_b32_dpp v20, v36 row_ror:2 row_mask:0xf bank_mask:0xf
	v_mov_b32_dpp v17, v37 row_ror:1 row_mask:0xf bank_mask:0xf
	v_mov_b32_dpp v21, v37 row_ror:2 row_mask:0xf bank_mask:0xf
	v_mov_b32_dpp v18, v38 row_ror:1 row_mask:0xf bank_mask:0xf
	v_mov_b32_dpp v22, v38 row_ror:2 row_mask:0xf bank_mask:0xf
	v_mov_b32_dpp v19, v39 row_ror:1 row_mask:0xf bank_mask:0xf
	v_mov_b32_dpp v23, v39 row_ror:2 row_mask:0xf bank_mask:0xf
	s_and_saveexec_b64 s[0:1], s[28:29]
	s_cbranch_execz .LBB0_726
	v_cndmask_b32_e64 v6, v14, v6, s[8:9]
	v_cndmask_b32_e64 v7, v15, v7, s[8:9]
	v_pk_mul_f32 v[6:7], v[78:79], v[6:7]
	v_cndmask_b32_e64 v2, v2, v10, s[6:7]
	v_cndmask_b32_e64 v3, v3, v11, s[6:7]
	v_pk_fma_f32 v[2:3], v[74:75], v[2:3], v[6:7]
	v_cndmask_b32_e64 v4, v12, v4, s[8:9]
	v_pk_fma_f32 v[2:3], v[26:27], v[82:83], v[2:3]
	v_cndmask_b32_e64 v5, v13, v5, s[8:9]
	v_mul_f32_e32 v6, 0xbfb8aa3b, v3
	v_exp_f32_e32 v6, v6
	v_pk_mul_f32 v[4:5], v[76:77], v[4:5]
	v_cndmask_b32_e64 v0, v0, v8, s[6:7]
	v_cndmask_b32_e64 v1, v1, v9, s[6:7]
	v_pk_fma_f32 v[0:1], v[72:73], v[0:1], v[4:5]
	v_add_f32_e32 v4, 1.0, v6
	v_mul_f32_e32 v5, 0xbfb8aa3b, v2
	v_rcp_f32_e32 v4, v4
	v_exp_f32_e32 v5, v5
	v_pk_fma_f32 v[0:1], v[24:25], v[80:81], v[0:1]
	v_cndmask_b32_e64 v20, v32, v20, s[8:9]
	v_mul_f32_e32 v3, v3, v4
	v_add_f32_e32 v4, 1.0, v5
	v_mul_f32_e32 v5, 0xbfb8aa3b, v1
	v_mul_f32_e32 v6, 0xbfb8aa3b, v0
	v_rcp_f32_e32 v4, v4
	v_exp_f32_e32 v5, v5
	v_exp_f32_e32 v6, v6
	v_cndmask_b32_e64 v21, v33, v21, s[8:9]
	v_mul_f32_e32 v2, v2, v4
	v_add_f32_e32 v4, 1.0, v5
	v_add_f32_e32 v5, 1.0, v6
	v_rcp_f32_e32 v4, v4
	v_rcp_f32_e32 v5, v5
	v_cndmask_b32_e64 v22, v34, v22, s[8:9]
	v_cndmask_b32_e64 v23, v35, v23, s[8:9]
	v_pk_mul_f32 v[20:21], v[84:85], v[20:21]
	v_pk_mul_f32 v[22:23], v[86:87], v[22:23]
	v_cndmask_b32_e64 v16, v16, v28, s[6:7]
	v_cndmask_b32_e64 v17, v17, v29, s[6:7]
	v_cndmask_b32_e64 v18, v18, v30, s[6:7]
	v_cndmask_b32_e64 v19, v19, v31, s[6:7]
	v_pk_fma_f32 v[18:19], v[90:91], v[18:19], v[22:23]
	v_pk_fma_f32 v[16:17], v[88:89], v[16:17], v[20:21]
	v_pk_fma_f32 v[18:19], v[38:39], v[94:95], v[18:19]
	v_pk_fma_f32 v[16:17], v[36:37], v[92:93], v[16:17]
	v_mul_f32_e32 v1, v1, v4
	v_mul_f32_e32 v0, v0, v5
	v_mul_f32_e32 v3, v3, v19
	v_mul_f32_e32 v2, v2, v18
	v_mul_f32_e32 v1, v1, v17
	v_mul_f32_e32 v0, v0, v16
	v_cvt_pk_bf16_f32 v0, v0, v1
	v_cvt_pk_bf16_f32 v1, v2, v3
	v_mov_b64_e32 v[2:3], s[30:31]
	v_mad_i64_i32 v[2:3], s[16:17], v137, s67, v[2:3]
	v_lshl_add_u64 v[2:3], v[192:193], 1, v[2:3]
	global_store_dwordx2 v[2:3], v[0:1], off offset:8
